# non-temporal (nt) loads for the read-once f32 weights streamed by the in-loop weight-transpose and shift-bias side work, so they do not displace reusable data in L2/MALL
# speedup vs baseline: 1.0102x; 1.0102x over previous
.LBB0_1912:
	s_lshl_b32 s66, s45, 6
	s_cmp_gt_i32 s45, 43
	s_mov_b64 s[6:7], -1
	s_cbranch_scc0 .LBB0_1996
	v_mov_b32_e32 v20, v228
	s_waitcnt lgkmcnt(0)
	v_and_b32_e32 v0, 0x3ff, v20
	v_cmp_lt_u32_e32 vcc, s92, v20
	v_lshlrev_b32_e32 v64, 2, v0
	s_barrier
	s_and_saveexec_b64 s[0:1], vcc
	s_xor_b64 s[6:7], exec, s[0:1]
	v_ashrrev_i32_e32 v0, 10, v20
	v_add_u32_e32 v0, -1, v0
	v_mul_hi_i32_i24_e32 v1, 0x6000, v0
	v_mul_i32_i24_e32 v0, 0x6000, v0
	v_lshl_add_u64 v[0:1], s[20:21], 0, v[0:1]
	v_lshl_add_u64 v[0:1], v[0:1], 0, v[64:65]
	s_andn2_saveexec_b64 s[6:7], s[6:7]
	v_lshl_add_u64 v[0:1], s[18:19], 0, v[64:65]
	s_or_b64 exec, exec, s[6:7]
	global_load_dword v4, v[0:1], off nt
	v_add_u32_e32 v21, 0x200, v20
	v_and_b32_e32 v0, 0x3ff, v21
	v_cmp_lt_u32_e32 vcc, s92, v21
	v_lshlrev_b32_e32 v0, 2, v0
	s_and_saveexec_b64 s[0:1], vcc
	s_xor_b64 s[6:7], exec, s[0:1]
	v_ashrrev_i32_e32 v1, 10, v21
	v_add_u32_e32 v1, -1, v1
	v_mul_hi_i32_i24_e32 v3, 0x6000, v1
	v_mul_i32_i24_e32 v2, 0x6000, v1
	v_lshl_add_u64 v[2:3], s[20:21], 0, v[2:3]
	v_mov_b32_e32 v1, v65
	v_lshl_add_u64 v[2:3], v[2:3], 0, v[0:1]
	s_andn2_saveexec_b64 s[6:7], s[6:7]
	v_mov_b32_e32 v1, v65
	v_lshl_add_u64 v[2:3], s[18:19], 0, v[0:1]
	s_or_b64 exec, exec, s[6:7]
	global_load_dword v5, v[2:3], off nt
	s_movk_i32 s0, 0xfc00
	v_cmp_gt_u32_e32 vcc, s0, v20
	s_and_saveexec_b64 s[0:1], vcc
	s_xor_b64 s[6:7], exec, s[0:1]
	v_add_u32_e32 v0, 0x400, v20
	v_ashrrev_i32_e32 v0, 10, v0
	v_add_u32_e32 v0, -1, v0
	v_mul_hi_i32_i24_e32 v1, 0x6000, v0
	v_mul_i32_i24_e32 v0, 0x6000, v0
	v_lshl_add_u64 v[0:1], s[20:21], 0, v[0:1]
	v_lshl_add_u64 v[0:1], v[0:1], 0, v[64:65]
	s_andn2_saveexec_b64 s[6:7], s[6:7]
	v_lshl_add_u64 v[0:1], s[18:19], 0, v[64:65]
	s_or_b64 exec, exec, s[6:7]
	global_load_dword v6, v[0:1], off nt
	v_add_u32_e32 v1, 0x600, v20
	v_and_b32_e32 v0, 0x3ff, v1
	v_cmp_lt_u32_e32 vcc, s92, v1
	v_lshlrev_b32_e32 v0, 2, v0
	s_and_saveexec_b64 s[0:1], vcc
	s_xor_b64 s[6:7], exec, s[0:1]
	v_ashrrev_i32_e32 v1, 10, v1
	v_add_u32_e32 v1, -1, v1
	v_mul_hi_i32_i24_e32 v3, 0x6000, v1
	v_mul_i32_i24_e32 v2, 0x6000, v1
	v_lshl_add_u64 v[2:3], s[20:21], 0, v[2:3]
	v_mov_b32_e32 v1, v65
	v_lshl_add_u64 v[2:3], v[2:3], 0, v[0:1]
	s_andn2_saveexec_b64 s[6:7], s[6:7]
	v_mov_b32_e32 v1, v65
	v_lshl_add_u64 v[2:3], s[18:19], 0, v[0:1]
	s_or_b64 exec, exec, s[6:7]
	global_load_dword v7, v[2:3], off nt
	v_add_u32_e32 v2, 0x800, v20
	v_cmp_lt_u32_e32 vcc, s92, v2
	s_and_saveexec_b64 s[0:1], vcc
	s_xor_b64 s[6:7], exec, s[0:1]
	v_ashrrev_i32_e32 v0, 10, v2
	v_add_u32_e32 v0, -1, v0
	v_mul_hi_i32_i24_e32 v1, 0x6000, v0
	v_mul_i32_i24_e32 v0, 0x6000, v0
	v_lshl_add_u64 v[0:1], s[20:21], 0, v[0:1]
	v_lshl_add_u64 v[0:1], v[0:1], 0, v[64:65]
	s_andn2_saveexec_b64 s[6:7], s[6:7]
	v_lshl_add_u64 v[0:1], s[18:19], 0, v[64:65]
	s_or_b64 exec, exec, s[6:7]
	global_load_dword v8, v[0:1], off nt
	v_add_u32_e32 v1, 0xa00, v20
	v_and_b32_e32 v0, 0x3ff, v1
	v_cmp_lt_u32_e32 vcc, s92, v1
	v_lshlrev_b32_e32 v0, 2, v0
	s_and_saveexec_b64 s[0:1], vcc
	s_xor_b64 s[6:7], exec, s[0:1]
	v_ashrrev_i32_e32 v1, 10, v1
	v_add_u32_e32 v1, -1, v1
	v_mul_hi_i32_i24_e32 v3, 0x6000, v1
	v_mul_i32_i24_e32 v2, 0x6000, v1
	v_lshl_add_u64 v[2:3], s[20:21], 0, v[2:3]
	v_mov_b32_e32 v1, v65
	v_lshl_add_u64 v[2:3], v[2:3], 0, v[0:1]
	s_andn2_saveexec_b64 s[6:7], s[6:7]
	v_mov_b32_e32 v1, v65
	v_lshl_add_u64 v[2:3], s[18:19], 0, v[0:1]
	s_or_b64 exec, exec, s[6:7]
	global_load_dword v9, v[2:3], off nt
	v_add_u32_e32 v2, 0xc00, v20
	v_cmp_lt_u32_e32 vcc, s92, v2
	s_and_saveexec_b64 s[0:1], vcc
	s_xor_b64 s[6:7], exec, s[0:1]
	v_ashrrev_i32_e32 v0, 10, v2
	v_add_u32_e32 v0, -1, v0
	v_mul_hi_i32_i24_e32 v1, 0x6000, v0
	v_mul_i32_i24_e32 v0, 0x6000, v0
	v_lshl_add_u64 v[0:1], s[20:21], 0, v[0:1]
	v_lshl_add_u64 v[0:1], v[0:1], 0, v[64:65]
	s_andn2_saveexec_b64 s[6:7], s[6:7]
	v_lshl_add_u64 v[0:1], s[18:19], 0, v[64:65]
	s_or_b64 exec, exec, s[6:7]
	global_load_dword v10, v[0:1], off nt
	v_add_u32_e32 v1, 0xe00, v20
	v_and_b32_e32 v0, 0x3ff, v1
	v_cmp_lt_u32_e32 vcc, s92, v1
	v_lshlrev_b32_e32 v0, 2, v0
	s_and_saveexec_b64 s[0:1], vcc
	s_xor_b64 s[6:7], exec, s[0:1]
	v_ashrrev_i32_e32 v1, 10, v1
	v_add_u32_e32 v1, -1, v1
	v_mul_hi_i32_i24_e32 v3, 0x6000, v1
	v_mul_i32_i24_e32 v2, 0x6000, v1
	v_lshl_add_u64 v[2:3], s[20:21], 0, v[2:3]
	v_mov_b32_e32 v1, v65
	v_lshl_add_u64 v[2:3], v[2:3], 0, v[0:1]
	s_andn2_saveexec_b64 s[6:7], s[6:7]
	v_mov_b32_e32 v1, v65
	v_lshl_add_u64 v[2:3], s[18:19], 0, v[0:1]
	s_or_b64 exec, exec, s[6:7]
	global_load_dword v11, v[2:3], off nt
	v_add_u32_e32 v2, 0x1000, v20
	v_cmp_lt_u32_e32 vcc, s92, v2
	s_and_saveexec_b64 s[0:1], vcc
	s_xor_b64 s[6:7], exec, s[0:1]
	v_ashrrev_i32_e32 v0, 10, v2
	v_add_u32_e32 v0, -1, v0
	v_mul_hi_i32_i24_e32 v1, 0x6000, v0
	v_mul_i32_i24_e32 v0, 0x6000, v0
	v_lshl_add_u64 v[0:1], s[20:21], 0, v[0:1]
	v_lshl_add_u64 v[0:1], v[0:1], 0, v[64:65]
	s_andn2_saveexec_b64 s[6:7], s[6:7]
	v_lshl_add_u64 v[0:1], s[18:19], 0, v[64:65]
	s_or_b64 exec, exec, s[6:7]
	global_load_dword v12, v[0:1], off nt
	v_add_u32_e32 v1, 0x1200, v20
	v_and_b32_e32 v0, 0x3ff, v1
	v_cmp_lt_u32_e32 vcc, s92, v1
	v_lshlrev_b32_e32 v0, 2, v0
	s_and_saveexec_b64 s[0:1], vcc
	s_xor_b64 s[6:7], exec, s[0:1]
	v_ashrrev_i32_e32 v1, 10, v1
	v_add_u32_e32 v1, -1, v1
	v_mul_hi_i32_i24_e32 v3, 0x6000, v1
	v_mul_i32_i24_e32 v2, 0x6000, v1
	v_lshl_add_u64 v[2:3], s[20:21], 0, v[2:3]
	v_mov_b32_e32 v1, v65
	v_lshl_add_u64 v[2:3], v[2:3], 0, v[0:1]
	s_andn2_saveexec_b64 s[6:7], s[6:7]
	v_mov_b32_e32 v1, v65
	v_lshl_add_u64 v[2:3], s[18:19], 0, v[0:1]
	s_or_b64 exec, exec, s[6:7]
	global_load_dword v13, v[2:3], off nt
	v_add_u32_e32 v2, 0x1400, v20
	v_cmp_lt_u32_e32 vcc, s92, v2
	s_and_saveexec_b64 s[0:1], vcc
	s_xor_b64 s[6:7], exec, s[0:1]
	v_ashrrev_i32_e32 v0, 10, v2
	v_add_u32_e32 v0, -1, v0
	v_mul_hi_i32_i24_e32 v1, 0x6000, v0
	v_mul_i32_i24_e32 v0, 0x6000, v0
	v_lshl_add_u64 v[0:1], s[20:21], 0, v[0:1]
	v_lshl_add_u64 v[0:1], v[0:1], 0, v[64:65]
	s_andn2_saveexec_b64 s[6:7], s[6:7]
	v_lshl_add_u64 v[0:1], s[18:19], 0, v[64:65]
	s_or_b64 exec, exec, s[6:7]
	global_load_dword v14, v[0:1], off nt
	v_add_u32_e32 v1, 0x1600, v20
	v_and_b32_e32 v0, 0x3ff, v1
	v_cmp_lt_u32_e32 vcc, s92, v1
	v_lshlrev_b32_e32 v0, 2, v0
	s_and_saveexec_b64 s[0:1], vcc
	s_xor_b64 s[6:7], exec, s[0:1]
	v_ashrrev_i32_e32 v1, 10, v1
	v_add_u32_e32 v1, -1, v1
	v_mul_hi_i32_i24_e32 v3, 0x6000, v1
	v_mul_i32_i24_e32 v2, 0x6000, v1
	v_lshl_add_u64 v[2:3], s[20:21], 0, v[2:3]
	v_mov_b32_e32 v1, v65
	v_lshl_add_u64 v[2:3], v[2:3], 0, v[0:1]
	s_andn2_saveexec_b64 s[6:7], s[6:7]
	v_mov_b32_e32 v1, v65
	v_lshl_add_u64 v[2:3], s[18:19], 0, v[0:1]
	s_or_b64 exec, exec, s[6:7]
	global_load_dword v15, v[2:3], off nt
	v_add_u32_e32 v2, 0x1800, v20
	v_cmp_lt_u32_e32 vcc, s92, v2
	s_and_saveexec_b64 s[0:1], vcc
	s_xor_b64 s[6:7], exec, s[0:1]
	v_ashrrev_i32_e32 v0, 10, v2
	v_add_u32_e32 v0, -1, v0
	v_mul_hi_i32_i24_e32 v1, 0x6000, v0
	v_mul_i32_i24_e32 v0, 0x6000, v0
	v_lshl_add_u64 v[0:1], s[20:21], 0, v[0:1]
	v_lshl_add_u64 v[0:1], v[0:1], 0, v[64:65]
	s_andn2_saveexec_b64 s[6:7], s[6:7]
	v_lshl_add_u64 v[0:1], s[18:19], 0, v[64:65]
	s_or_b64 exec, exec, s[6:7]
	global_load_dword v16, v[0:1], off nt
	v_add_u32_e32 v1, 0x1a00, v20
	v_and_b32_e32 v0, 0x3ff, v1
	v_cmp_lt_u32_e32 vcc, s92, v1
	v_lshlrev_b32_e32 v0, 2, v0
	s_and_saveexec_b64 s[0:1], vcc
	s_xor_b64 s[6:7], exec, s[0:1]
	v_ashrrev_i32_e32 v1, 10, v1
	v_add_u32_e32 v1, -1, v1
	v_mul_hi_i32_i24_e32 v3, 0x6000, v1
	v_mul_i32_i24_e32 v2, 0x6000, v1
	v_lshl_add_u64 v[2:3], s[20:21], 0, v[2:3]
	v_mov_b32_e32 v1, v65
	v_lshl_add_u64 v[2:3], v[2:3], 0, v[0:1]
	s_andn2_saveexec_b64 s[6:7], s[6:7]
	v_mov_b32_e32 v1, v65
	v_lshl_add_u64 v[2:3], s[18:19], 0, v[0:1]
	s_or_b64 exec, exec, s[6:7]
	global_load_dword v17, v[2:3], off nt
	v_add_u32_e32 v2, 0x1c00, v20
	v_cmp_lt_u32_e32 vcc, s92, v2
	s_and_saveexec_b64 s[0:1], vcc
	s_xor_b64 s[6:7], exec, s[0:1]
	v_ashrrev_i32_e32 v0, 10, v2
	v_add_u32_e32 v0, -1, v0
	v_mul_hi_i32_i24_e32 v1, 0x6000, v0
	v_mul_i32_i24_e32 v0, 0x6000, v0
	v_lshl_add_u64 v[0:1], s[20:21], 0, v[0:1]
	v_lshl_add_u64 v[0:1], v[0:1], 0, v[64:65]
	s_andn2_saveexec_b64 s[6:7], s[6:7]
	v_lshl_add_u64 v[0:1], s[18:19], 0, v[64:65]
	s_or_b64 exec, exec, s[6:7]
	global_load_dword v18, v[0:1], off nt
	v_add_u32_e32 v1, 0x1e00, v20
	v_and_b32_e32 v0, 0x3ff, v1
	v_cmp_lt_u32_e32 vcc, s92, v1
	v_lshlrev_b32_e32 v0, 2, v0
	s_and_saveexec_b64 s[0:1], vcc
	s_xor_b64 s[6:7], exec, s[0:1]
	v_ashrrev_i32_e32 v1, 10, v1
	v_add_u32_e32 v1, -1, v1
	v_mul_hi_i32_i24_e32 v3, 0x6000, v1
	v_mul_i32_i24_e32 v2, 0x6000, v1
	v_lshl_add_u64 v[2:3], s[20:21], 0, v[2:3]
	v_mov_b32_e32 v1, v65
	v_lshl_add_u64 v[2:3], v[2:3], 0, v[0:1]
	s_andn2_saveexec_b64 s[6:7], s[6:7]
	v_mov_b32_e32 v1, v65
	v_lshl_add_u64 v[2:3], s[18:19], 0, v[0:1]
	s_or_b64 exec, exec, s[6:7]
	global_load_dword v2, v[2:3], off nt
	v_add_u32_e32 v3, 0x2000, v20
	v_cmp_lt_u32_e32 vcc, s92, v3
	s_and_saveexec_b64 s[0:1], vcc
	s_xor_b64 s[6:7], exec, s[0:1]
	v_ashrrev_i32_e32 v0, 10, v3
	v_add_u32_e32 v0, -1, v0
	v_mul_hi_i32_i24_e32 v1, 0x6000, v0
	v_mul_i32_i24_e32 v0, 0x6000, v0
	v_lshl_add_u64 v[0:1], s[20:21], 0, v[0:1]
	v_lshl_add_u64 v[0:1], v[0:1], 0, v[64:65]
	s_andn2_saveexec_b64 s[6:7], s[6:7]
	v_lshl_add_u64 v[0:1], s[18:19], 0, v[64:65]
	s_or_b64 exec, exec, s[6:7]
	global_load_dword v3, v[0:1], off nt
	v_add_u32_e32 v19, 0x2200, v20
	v_and_b32_e32 v0, 0x3ff, v19
	v_cmp_lt_u32_e32 vcc, s92, v19
	v_lshlrev_b32_e32 v64, 2, v0
	s_and_saveexec_b64 s[0:1], vcc
	s_xor_b64 s[6:7], exec, s[0:1]
	v_ashrrev_i32_e32 v0, 10, v19
	v_add_u32_e32 v0, -1, v0
	v_mul_hi_i32_i24_e32 v1, 0x6000, v0
	v_mul_i32_i24_e32 v0, 0x6000, v0
	v_lshl_add_u64 v[0:1], s[20:21], 0, v[0:1]
	v_lshl_add_u64 v[0:1], v[0:1], 0, v[64:65]
	s_andn2_saveexec_b64 s[6:7], s[6:7]
	v_lshl_add_u64 v[0:1], s[18:19], 0, v[64:65]
	s_or_b64 exec, exec, s[6:7]
	global_load_dword v0, v[0:1], off nt
	v_lshl_add_u32 v1, v20, 2, 0
	v_ashrrev_i32_e32 v37, 6, v20
	v_and_b32_e32 v31, 63, v20
	v_lshlrev_b32_e32 v64, 2, v31
	v_readlane_b32 s0, v255, 13
	v_readlane_b32 s84, v254, 2
	v_readlane_b32 s1, v255, 14
	v_readlane_b32 s88, v254, 6
	v_readlane_b32 s89, v254, 7
	v_lshl_add_u32 v49, v37, 9, 0
	s_movk_i32 s4, 0xffe0
	v_readlane_b32 s85, v254, 3
	v_readlane_b32 s86, v254, 4
	v_readlane_b32 s87, v254, 5
	v_readlane_b32 s90, v254, 8
	v_readlane_b32 s91, v254, 9
	s_waitcnt vmcnt(0)
	ds_write2st64_b32 v1, v4, v5 offset1:8
	ds_write2st64_b32 v1, v6, v7 offset0:16 offset1:24
	ds_write2st64_b32 v1, v8, v9 offset0:32 offset1:40
	ds_write2st64_b32 v1, v10, v11 offset0:48 offset1:56
	ds_write2st64_b32 v1, v12, v13 offset0:64 offset1:72
	ds_write2st64_b32 v1, v14, v15 offset0:80 offset1:88
	ds_write2st64_b32 v1, v16, v17 offset0:96 offset1:104
	ds_write2st64_b32 v1, v18, v2 offset0:112 offset1:120
	ds_write2st64_b32 v1, v3, v0 offset0:128 offset1:136
	v_lshlrev_b32_e32 v0, 7, v37
	v_ashrrev_i32_e32 v1, 31, v0
	v_lshlrev_b64 v[0:1], 14, v[0:1]
	v_lshl_add_u64 v[22:23], s[72:73], 0, v[0:1]
	v_lshl_add_u64 v[0:1], s[96:97], 2, v[64:65]
	v_mov_b32_e32 v8, 0
	v_lshl_add_u64 v[24:25], s[0:1], 0, v[0:1]
	v_lshl_add_u64 v[26:27], s[88:89], 0, v[0:1]
	v_mov_b32_e32 v9, v8
	v_mov_b32_e32 v12, v8
	v_mov_b32_e32 v13, v8
	v_mov_b32_e32 v32, v8
	v_mov_b32_e32 v33, v8
	v_mov_b32_e32 v44, v8
	v_mov_b32_e32 v45, v8
	v_mov_b32_e32 v29, v8
	s_waitcnt lgkmcnt(0)
	s_barrier
.LBB0_1986:
	v_lshl_add_u64 v[0:1], v[24:25], 0, v[22:23]
	global_load_dword v80, v[0:1], off nt
	v_lshl_add_u64 v[0:1], v[26:27], 0, v[22:23]
	v_add_co_u32_e32 v2, vcc, 0x1004000, v0
	v_add_u32_e32 v51, 0x702c, v49
	s_nop 0
	v_addc_co_u32_e32 v3, vcc, 0, v1, vcc
	global_load_dword v82, v[2:3], off nt
	v_add_co_u32_e32 v2, vcc, 0x1008000, v0
	v_add_u32_e32 v55, 0x2034, v49
	s_nop 0
	v_addc_co_u32_e32 v3, vcc, 0, v1, vcc
	global_load_dword v84, v[2:3], off nt
	v_add_co_u32_e32 v2, vcc, 0x100c000, v0
	v_add_u32_e32 v53, 0x1034, v49
	s_nop 0
	v_addc_co_u32_e32 v3, vcc, 0, v1, vcc
	global_load_dword v86, v[2:3], off nt
	v_add_co_u32_e32 v2, vcc, 0x1010000, v0
	v_add_u32_e32 v59, 0x4034, v49
	s_nop 0
	v_addc_co_u32_e32 v3, vcc, 0, v1, vcc
	global_load_dword v68, v[2:3], off nt
	v_add_co_u32_e32 v2, vcc, 0x1014000, v0
	v_add_u32_e32 v57, 0x3034, v49
	s_nop 0
	v_addc_co_u32_e32 v3, vcc, 0, v1, vcc
	global_load_dword v70, v[2:3], off nt
	v_add_co_u32_e32 v2, vcc, 0x1018000, v0
	v_add_u32_e32 v63, 0x6034, v49
	s_nop 0
	v_addc_co_u32_e32 v3, vcc, 0, v1, vcc
	global_load_dword v72, v[2:3], off nt
	v_add_co_u32_e32 v2, vcc, 0x101c000, v0
	v_add_u32_e32 v61, 0x5034, v49
	s_nop 0
	v_addc_co_u32_e32 v3, vcc, 0, v1, vcc
	global_load_dword v76, v[2:3], off nt
	v_add_co_u32_e32 v2, vcc, 0x1020000, v0
	v_add_u32_e32 v67, 0x7034, v49
	s_nop 0
	v_addc_co_u32_e32 v3, vcc, 0, v1, vcc
	global_load_dword v74, v[2:3], off nt
	v_add_co_u32_e32 v2, vcc, 0x1024000, v0
	v_add_u32_e32 v47, 0x602c, v49
	s_nop 0
	v_addc_co_u32_e32 v3, vcc, 0, v1, vcc
	global_load_dword v78, v[2:3], off nt
	v_add_co_u32_e32 v2, vcc, 0x1028000, v0
	s_add_i32 s4, s4, 32
	s_nop 0
	v_addc_co_u32_e32 v3, vcc, 0, v1, vcc
	global_load_dword v50, v[2:3], off nt
	v_add_co_u32_e32 v2, vcc, 0x102c000, v0
	s_mov_b64 s[0:1], 0x80000
	s_nop 0
	v_addc_co_u32_e32 v3, vcc, 0, v1, vcc
	global_load_dword v48, v[2:3], off nt
	v_add_co_u32_e32 v2, vcc, 0x1030000, v0
	v_lshl_add_u64 v[22:23], v[22:23], 0, s[0:1]
	s_nop 0
	v_addc_co_u32_e32 v3, vcc, 0, v1, vcc
	global_load_dword v54, v[2:3], off nt
	v_add_co_u32_e32 v2, vcc, 0x1034000, v0
	s_cmpk_gt_u32 s4, 0x5f
	s_nop 0
	v_addc_co_u32_e32 v3, vcc, 0, v1, vcc
	global_load_dword v52, v[2:3], off nt
	v_add_co_u32_e32 v2, vcc, 0x1038000, v0
	s_nop 1
	v_addc_co_u32_e32 v3, vcc, 0, v1, vcc
	global_load_dword v58, v[2:3], off nt
	v_add_co_u32_e32 v2, vcc, 0x103c000, v0
	s_nop 1
	v_addc_co_u32_e32 v3, vcc, 0, v1, vcc
	global_load_dword v56, v[2:3], off nt
	v_add_co_u32_e32 v2, vcc, 0x1040000, v0
	s_nop 1
	v_addc_co_u32_e32 v3, vcc, 0, v1, vcc
	global_load_dword v62, v[2:3], off nt
	v_add_co_u32_e32 v2, vcc, 0x1044000, v0
	s_nop 1
	v_addc_co_u32_e32 v3, vcc, 0, v1, vcc
	global_load_dword v60, v[2:3], off nt
	v_add_co_u32_e32 v2, vcc, 0x1048000, v0
	s_nop 1
	v_addc_co_u32_e32 v3, vcc, 0, v1, vcc
	global_load_dword v66, v[2:3], off nt
	v_add_co_u32_e32 v2, vcc, 0x104c000, v0
	s_nop 1
	v_addc_co_u32_e32 v3, vcc, 0, v1, vcc
	global_load_dword v64, v[2:3], off nt
	v_add_co_u32_e32 v2, vcc, 0x1050000, v0
	s_nop 1
	v_addc_co_u32_e32 v3, vcc, 0, v1, vcc
	global_load_dword v46, v[2:3], off nt
	v_add_co_u32_e32 v2, vcc, 0x1054000, v0
	s_nop 1
	v_addc_co_u32_e32 v3, vcc, 0, v1, vcc
	global_load_dword v36, v[2:3], off nt
	v_add_co_u32_e32 v2, vcc, 0x1058000, v0
	s_nop 1
	v_addc_co_u32_e32 v3, vcc, 0, v1, vcc
	global_load_dword v34, v[2:3], off nt
	v_add_co_u32_e32 v2, vcc, 0x105c000, v0
	s_nop 1
	v_addc_co_u32_e32 v3, vcc, 0, v1, vcc
	global_load_dword v35, v[2:3], off nt
	v_add_co_u32_e32 v2, vcc, 0x1060000, v0
	s_nop 1
	v_addc_co_u32_e32 v3, vcc, 0, v1, vcc
	global_load_dword v38, v[2:3], off nt
	v_add_co_u32_e32 v2, vcc, 0x1064000, v0
	s_nop 1
	v_addc_co_u32_e32 v3, vcc, 0, v1, vcc
	global_load_dword v39, v[2:3], off nt
	v_add_co_u32_e32 v2, vcc, 0x1068000, v0
	s_nop 1
	v_addc_co_u32_e32 v3, vcc, 0, v1, vcc
	global_load_dword v40, v[2:3], off nt
	v_add_co_u32_e32 v2, vcc, 0x106c000, v0
	s_nop 1
	v_addc_co_u32_e32 v3, vcc, 0, v1, vcc
	global_load_dword v41, v[2:3], off nt
	v_add_co_u32_e32 v2, vcc, 0x1070000, v0
	s_nop 1
	v_addc_co_u32_e32 v3, vcc, 0, v1, vcc
	global_load_dword v42, v[2:3], off nt
	v_add_co_u32_e32 v2, vcc, 0x1074000, v0
	s_nop 1
	v_addc_co_u32_e32 v3, vcc, 0, v1, vcc
	global_load_dword v43, v[2:3], off nt
	v_add_co_u32_e32 v2, vcc, 0x1078000, v0
	s_nop 1
	v_addc_co_u32_e32 v3, vcc, 0, v1, vcc
	v_add_co_u32_e32 v0, vcc, 0x107c000, v0
	global_load_dword v28, v[2:3], off nt
	s_nop 0
	v_addc_co_u32_e32 v1, vcc, 0, v1, vcc
	global_load_dword v30, v[0:1], off nt
	ds_read_b128 v[0:3], v49 offset:32768
	s_waitcnt vmcnt(31) lgkmcnt(0)
	v_fmac_f32_e32 v29, v80, v0
	s_waitcnt vmcnt(30)
	v_fmac_f32_e32 v29, v82, v1
	s_waitcnt vmcnt(29)
	v_fmac_f32_e32 v29, v84, v2
	s_waitcnt vmcnt(28)
	v_fmac_f32_e32 v29, v86, v3
	ds_read_b128 v[0:3], v49 offset:32784
	s_waitcnt vmcnt(27) lgkmcnt(0)
	v_fmac_f32_e32 v29, v68, v0
	s_waitcnt vmcnt(26)
	v_fmac_f32_e32 v29, v70, v1
	s_waitcnt vmcnt(25)
	v_fmac_f32_e32 v29, v72, v2
	s_waitcnt vmcnt(24)
	v_fmac_f32_e32 v29, v76, v3
	ds_read_b128 v[0:3], v49 offset:32800
	ds_read_b128 v[14:17], v49
	ds_read_b128 v[88:91], v49 offset:16
	ds_read_b96 v[4:6], v49 offset:32
	ds_read_b128 v[92:95], v49 offset:4096
	s_waitcnt lgkmcnt(3)
	v_mov_b32_e32 v10, v14
	s_waitcnt vmcnt(23)
	v_fmac_f32_e32 v29, v74, v0
	s_waitcnt lgkmcnt(0)
	v_mov_b32_e32 v11, v92
	v_pk_fma_f32 v[8:9], v[80:81], v[10:11], v[8:9] op_sel_hi:[0,1,1]
	v_mov_b32_e32 v92, v15
	v_pk_fma_f32 v[8:9], v[82:83], v[92:93], v[8:9] op_sel_hi:[0,1,1]
	v_mov_b32_e32 v10, v16
	v_mov_b32_e32 v11, v94
	v_pk_fma_f32 v[8:9], v[84:85], v[10:11], v[8:9] op_sel_hi:[0,1,1]
	v_mov_b32_e32 v94, v17
	v_pk_fma_f32 v[14:15], v[86:87], v[94:95], v[8:9] op_sel_hi:[0,1,1]
	ds_read_b128 v[8:11], v49 offset:4112
	v_mov_b32_e32 v16, v88
	s_waitcnt vmcnt(22)
	v_fmac_f32_e32 v29, v78, v1
	s_waitcnt vmcnt(21)
	v_fmac_f32_e32 v29, v50, v2
	s_waitcnt vmcnt(20)
	v_fmac_f32_e32 v29, v48, v3
	s_waitcnt lgkmcnt(0)
	v_mov_b32_e32 v17, v8
	v_pk_fma_f32 v[14:15], v[68:69], v[16:17], v[14:15] op_sel_hi:[0,1,1]
	v_mov_b32_e32 v8, v89
	v_pk_fma_f32 v[8:9], v[70:71], v[8:9], v[14:15] op_sel_hi:[0,1,1]
	v_mov_b32_e32 v14, v90
	v_mov_b32_e32 v15, v10
	v_pk_fma_f32 v[8:9], v[72:73], v[14:15], v[8:9] op_sel_hi:[0,1,1]
	v_mov_b32_e32 v10, v91
	v_pk_fma_f32 v[14:15], v[76:77], v[10:11], v[8:9] op_sel_hi:[0,1,1]
	ds_read_b96 v[8:10], v49 offset:4128
	v_mov_b32_e32 v16, v4
	s_waitcnt lgkmcnt(0)
	v_mov_b32_e32 v17, v8
	v_pk_fma_f32 v[14:15], v[74:75], v[16:17], v[14:15] op_sel_hi:[0,1,1]
	v_mov_b32_e32 v8, v5
	v_pk_fma_f32 v[4:5], v[78:79], v[8:9], v[14:15] op_sel_hi:[0,1,1]
	ds_read_b128 v[14:17], v49 offset:8192
	ds_read_b128 v[88:91], v49 offset:12288
	s_waitcnt lgkmcnt(1)
	v_mov_b32_e32 v8, v14
	s_waitcnt lgkmcnt(0)
	v_mov_b32_e32 v9, v88
	v_pk_fma_f32 v[8:9], v[80:81], v[8:9], v[12:13] op_sel_hi:[0,1,1]
	v_mov_b32_e32 v88, v15
	v_pk_fma_f32 v[8:9], v[82:83], v[88:89], v[8:9] op_sel_hi:[0,1,1]
	v_mov_b32_e32 v12, v16
	v_mov_b32_e32 v13, v90
	v_pk_fma_f32 v[8:9], v[84:85], v[12:13], v[8:9] op_sel_hi:[0,1,1]
	v_mov_b32_e32 v90, v17
	ds_read_b128 v[12:15], v49 offset:8208
	ds_read_b128 v[16:19], v49 offset:12304
	v_pk_fma_f32 v[8:9], v[86:87], v[90:91], v[8:9] op_sel_hi:[0,1,1]
	s_waitcnt lgkmcnt(1)
	v_mov_b32_e32 v88, v12
	s_waitcnt lgkmcnt(0)
	v_mov_b32_e32 v89, v16
	v_pk_fma_f32 v[8:9], v[68:69], v[88:89], v[8:9] op_sel_hi:[0,1,1]
	v_mov_b32_e32 v16, v13
	v_pk_fma_f32 v[8:9], v[70:71], v[16:17], v[8:9] op_sel_hi:[0,1,1]
	v_mov_b32_e32 v12, v14
	v_mov_b32_e32 v13, v18
	v_pk_fma_f32 v[8:9], v[72:73], v[12:13], v[8:9] op_sel_hi:[0,1,1]
	v_mov_b32_e32 v18, v15
	v_pk_fma_f32 v[8:9], v[76:77], v[18:19], v[8:9] op_sel_hi:[0,1,1]
	ds_read_b96 v[12:14], v49 offset:8224
	ds_read_b96 v[16:18], v49 offset:12320
	v_add_u32_e32 v19, 0x302c, v49
	s_waitcnt lgkmcnt(1)
	v_mov_b32_e32 v88, v12
	s_waitcnt lgkmcnt(0)
	v_mov_b32_e32 v89, v16
	v_pk_fma_f32 v[8:9], v[74:75], v[88:89], v[8:9] op_sel_hi:[0,1,1]
	ds_read_b128 v[88:91], v49 offset:16384
	ds_read_b128 v[92:95], v49 offset:20480
	v_mov_b32_e32 v16, v13
	v_pk_fma_f32 v[12:13], v[78:79], v[16:17], v[8:9] op_sel_hi:[0,1,1]
	v_mov_b32_e32 v11, v18
	s_waitcnt lgkmcnt(1)
	v_mov_b32_e32 v8, v88
	s_waitcnt lgkmcnt(0)
	v_mov_b32_e32 v9, v92
	v_pk_fma_f32 v[8:9], v[80:81], v[8:9], v[32:33] op_sel_hi:[0,1,1]
	v_mov_b32_e32 v92, v89
	v_pk_fma_f32 v[8:9], v[82:83], v[92:93], v[8:9] op_sel_hi:[0,1,1]
	v_mov_b32_e32 v16, v90
	v_mov_b32_e32 v17, v94
	v_pk_fma_f32 v[8:9], v[84:85], v[16:17], v[8:9] op_sel_hi:[0,1,1]
	v_mov_b32_e32 v94, v91
	v_pk_fma_f32 v[8:9], v[86:87], v[94:95], v[8:9] op_sel_hi:[0,1,1]
	ds_read_b128 v[88:91], v49 offset:16400
	ds_read_b128 v[92:95], v49 offset:20496
	v_add_u32_e32 v18, 0x202c, v49
	s_waitcnt lgkmcnt(1)
	v_mov_b32_e32 v16, v88
	s_waitcnt lgkmcnt(0)
	v_mov_b32_e32 v17, v92
	v_pk_fma_f32 v[8:9], v[68:69], v[16:17], v[8:9] op_sel_hi:[0,1,1]
	v_mov_b32_e32 v92, v89
	v_pk_fma_f32 v[8:9], v[70:71], v[92:93], v[8:9] op_sel_hi:[0,1,1]
	v_mov_b32_e32 v16, v90
	v_mov_b32_e32 v17, v94
	v_pk_fma_f32 v[8:9], v[72:73], v[16:17], v[8:9] op_sel_hi:[0,1,1]
	v_mov_b32_e32 v94, v91
	v_pk_fma_f32 v[8:9], v[76:77], v[94:95], v[8:9] op_sel_hi:[0,1,1]
	ds_read_b96 v[94:96], v49 offset:16416
	ds_read_b96 v[98:100], v49 offset:20512
	s_waitcnt lgkmcnt(1)
	v_mov_b32_e32 v16, v94
	s_waitcnt lgkmcnt(0)
	v_mov_b32_e32 v17, v98
	v_mov_b32_e32 v98, v95
	ds_read_b128 v[88:91], v49 offset:24576
	ds_read_b128 v[92:95], v49 offset:28672
	v_pk_fma_f32 v[8:9], v[74:75], v[16:17], v[8:9] op_sel_hi:[0,1,1]
	v_pk_fma_f32 v[16:17], v[78:79], v[98:99], v[8:9] op_sel_hi:[0,1,1]
	v_mov_b32_e32 v7, v100
	s_waitcnt lgkmcnt(1)
	v_mov_b32_e32 v8, v88
	s_waitcnt lgkmcnt(0)
	v_mov_b32_e32 v9, v92
	v_pk_fma_f32 v[8:9], v[80:81], v[8:9], v[44:45] op_sel_hi:[0,1,1]
	v_mov_b32_e32 v92, v89
	v_pk_fma_f32 v[8:9], v[82:83], v[92:93], v[8:9] op_sel_hi:[0,1,1]
	v_mov_b32_e32 v32, v90
	v_mov_b32_e32 v33, v94
	v_pk_fma_f32 v[8:9], v[84:85], v[32:33], v[8:9] op_sel_hi:[0,1,1]
	v_mov_b32_e32 v94, v91
	v_pk_fma_f32 v[8:9], v[86:87], v[94:95], v[8:9] op_sel_hi:[0,1,1]
	ds_read_b128 v[80:83], v49 offset:24592
	ds_read_b128 v[84:87], v49 offset:28688
	v_add_u32_e32 v44, 0x402c, v49
	v_add_u32_e32 v45, 0x502c, v49
	v_add_u32_e32 v88, 0x604c, v49
	s_waitcnt lgkmcnt(1)
	v_mov_b32_e32 v32, v80
	s_waitcnt lgkmcnt(0)
	v_mov_b32_e32 v33, v84
	v_pk_fma_f32 v[8:9], v[68:69], v[32:33], v[8:9] op_sel_hi:[0,1,1]
	v_mov_b32_e32 v84, v81
	v_pk_fma_f32 v[8:9], v[70:71], v[84:85], v[8:9] op_sel_hi:[0,1,1]
	v_mov_b32_e32 v32, v82
	ds_read_b96 v[68:70], v49 offset:24608
	ds_read_b96 v[80:82], v49 offset:28704
	v_mov_b32_e32 v33, v86
	v_pk_fma_f32 v[8:9], v[72:73], v[32:33], v[8:9] op_sel_hi:[0,1,1]
	v_mov_b32_e32 v86, v83
	s_waitcnt lgkmcnt(1)
	v_mov_b32_e32 v32, v68
	s_waitcnt lgkmcnt(0)
	v_mov_b32_e32 v33, v80
	v_mov_b32_e32 v80, v69
	v_mov_b32_e32 v0, v70
	ds_read_b128 v[68:71], v49 offset:32816
	v_pk_fma_f32 v[8:9], v[76:77], v[86:87], v[8:9] op_sel_hi:[0,1,1]
	v_pk_fma_f32 v[8:9], v[74:75], v[32:33], v[8:9] op_sel_hi:[0,1,1]
	v_pk_fma_f32 v[32:33], v[78:79], v[80:81], v[8:9] op_sel_hi:[0,1,1]
	v_mov_b32_e32 v8, v6
	s_waitcnt vmcnt(19) lgkmcnt(0)
	v_fmac_f32_e32 v29, v54, v68
	s_waitcnt vmcnt(18)
	v_fmac_f32_e32 v29, v52, v69
	v_mov_b32_e32 v9, v10
	s_waitcnt vmcnt(17)
	v_fmac_f32_e32 v29, v58, v70
	v_mov_b32_e32 v10, v14
	v_add_u32_e32 v14, 0x102c, v49
	s_waitcnt vmcnt(16)
	v_fmac_f32_e32 v29, v56, v71
	ds_read_b128 v[68:71], v49 offset:32832
	v_pk_fma_f32 v[2:3], v[50:51], v[8:9], v[4:5] op_sel_hi:[0,1,1]
	ds_read2_b32 v[4:5], v49 offset0:11 offset1:12
	ds_read2_b32 v[8:9], v14 offset1:1
	v_add_u32_e32 v72, 0x103c, v49
	v_add_u32_e32 v73, 0x203c, v49
	s_waitcnt vmcnt(15) lgkmcnt(2)
	v_fmac_f32_e32 v29, v62, v68
	s_waitcnt lgkmcnt(1)
	v_mov_b32_e32 v14, v4
	s_waitcnt lgkmcnt(0)
	v_mov_b32_e32 v15, v8
	v_pk_fma_f32 v[2:3], v[48:49], v[14:15], v[2:3] op_sel_hi:[0,1,1]
	v_mov_b32_e32 v8, v5
	v_pk_fma_f32 v[2:3], v[54:55], v[8:9], v[2:3] op_sel_hi:[0,1,1]
	ds_read2_b32 v[4:5], v49 offset0:13 offset1:14
	ds_read2_b32 v[8:9], v53 offset1:1
	v_add_u32_e32 v68, 0x1044, v49
	s_waitcnt vmcnt(14)
	v_fmac_f32_e32 v29, v60, v69
	v_add_u32_e32 v69, 0x104c, v49
	s_waitcnt lgkmcnt(1)
	v_mov_b32_e32 v14, v4
	s_waitcnt lgkmcnt(0)
	v_mov_b32_e32 v15, v8
	v_pk_fma_f32 v[2:3], v[52:53], v[14:15], v[2:3] op_sel_hi:[0,1,1]
	v_mov_b32_e32 v8, v5
	v_pk_fma_f32 v[2:3], v[58:59], v[8:9], v[2:3] op_sel_hi:[0,1,1]
	ds_read2_b32 v[4:5], v49 offset0:15 offset1:16
	ds_read2_b32 v[8:9], v72 offset1:1
	v_add_u32_e32 v74, 0x303c, v49
	v_add_u32_e32 v79, 0x2044, v49
	v_add_u32_e32 v80, 0x3044, v49
	s_waitcnt lgkmcnt(1)
	v_mov_b32_e32 v14, v4
	s_waitcnt lgkmcnt(0)
	v_mov_b32_e32 v15, v8
	v_pk_fma_f32 v[2:3], v[56:57], v[14:15], v[2:3] op_sel_hi:[0,1,1]
	v_mov_b32_e32 v8, v5
	v_pk_fma_f32 v[2:3], v[62:63], v[8:9], v[2:3] op_sel_hi:[0,1,1]
	ds_read2_b32 v[4:5], v49 offset0:17 offset1:18
	ds_read2_b32 v[8:9], v68 offset1:1
	s_waitcnt vmcnt(13)
	v_fmac_f32_e32 v29, v66, v70
	v_add_u32_e32 v70, 0x204c, v49
	v_add_u32_e32 v85, 0x304c, v49
	s_waitcnt lgkmcnt(1)
	v_mov_b32_e32 v14, v4
	s_waitcnt lgkmcnt(0)
	v_mov_b32_e32 v15, v8
	v_pk_fma_f32 v[2:3], v[60:61], v[14:15], v[2:3] op_sel_hi:[0,1,1]
	v_mov_b32_e32 v8, v5
	v_pk_fma_f32 v[2:3], v[66:67], v[8:9], v[2:3] op_sel_hi:[0,1,1]
	ds_read2_b32 v[4:5], v49 offset0:19 offset1:20
	ds_read2_b32 v[8:9], v69 offset1:1
	v_mov_b32_e32 v6, v96
	v_add_u32_e32 v75, 0x403c, v49
	v_add_u32_e32 v76, 0x503c, v49
	s_waitcnt lgkmcnt(1)
	v_mov_b32_e32 v14, v4
	s_waitcnt lgkmcnt(0)
	v_mov_b32_e32 v15, v8
	s_waitcnt vmcnt(12)
	v_pk_fma_f32 v[2:3], v[64:65], v[14:15], v[2:3] op_sel_hi:[0,1,1]
	v_mov_b32_e32 v8, v5
	s_waitcnt vmcnt(11)
	v_pk_fma_f32 v[8:9], v[46:47], v[8:9], v[2:3] op_sel_hi:[0,1,1]
	v_pk_fma_f32 v[2:3], v[50:51], v[10:11], v[12:13] op_sel_hi:[0,1,1]
	ds_read2_b32 v[4:5], v18 offset1:1
	ds_read2_b32 v[10:11], v19 offset1:1
	v_add_u32_e32 v81, 0x4044, v49
	v_mov_b32_e32 v1, v82
	v_add_u32_e32 v82, 0x5044, v49
	s_waitcnt lgkmcnt(1)
	v_mov_b32_e32 v12, v4
	s_waitcnt lgkmcnt(0)
	v_mov_b32_e32 v13, v10
	v_pk_fma_f32 v[2:3], v[48:49], v[12:13], v[2:3] op_sel_hi:[0,1,1]
	v_mov_b32_e32 v10, v5
	v_pk_fma_f32 v[2:3], v[54:55], v[10:11], v[2:3] op_sel_hi:[0,1,1]
	ds_read2_b32 v[4:5], v55 offset1:1
	ds_read2_b32 v[10:11], v57 offset1:1
	v_add_u32_e32 v86, 0x404c, v49
	v_add_u32_e32 v87, 0x504c, v49
	v_pk_fma_f32 v[0:1], v[50:51], v[0:1], v[32:33] op_sel_hi:[0,1,1]
	s_waitcnt lgkmcnt(1)
	v_mov_b32_e32 v12, v4
	s_waitcnt lgkmcnt(0)
	v_mov_b32_e32 v13, v10
	v_pk_fma_f32 v[2:3], v[52:53], v[12:13], v[2:3] op_sel_hi:[0,1,1]
	v_mov_b32_e32 v10, v5
	v_pk_fma_f32 v[2:3], v[58:59], v[10:11], v[2:3] op_sel_hi:[0,1,1]
	ds_read2_b32 v[4:5], v73 offset1:1
	ds_read2_b32 v[10:11], v74 offset1:1
	v_add_u32_e32 v77, 0x603c, v49
	v_add_u32_e32 v78, 0x703c, v49
	v_add_u32_e32 v83, 0x6044, v49
	s_waitcnt lgkmcnt(1)
	v_mov_b32_e32 v12, v4
	s_waitcnt lgkmcnt(0)
	v_mov_b32_e32 v13, v10
	v_pk_fma_f32 v[2:3], v[56:57], v[12:13], v[2:3] op_sel_hi:[0,1,1]
	v_mov_b32_e32 v10, v5
	v_pk_fma_f32 v[2:3], v[62:63], v[10:11], v[2:3] op_sel_hi:[0,1,1]
	ds_read2_b32 v[4:5], v79 offset1:1
	ds_read2_b32 v[10:11], v80 offset1:1
	v_add_u32_e32 v84, 0x7044, v49
	v_add_u32_e32 v89, 0x704c, v49
	v_fmac_f32_e32 v29, v64, v71
	s_waitcnt lgkmcnt(1)
	v_mov_b32_e32 v12, v4
	s_waitcnt lgkmcnt(0)
	v_mov_b32_e32 v13, v10
	v_pk_fma_f32 v[2:3], v[60:61], v[12:13], v[2:3] op_sel_hi:[0,1,1]
	v_mov_b32_e32 v10, v5
	v_pk_fma_f32 v[2:3], v[66:67], v[10:11], v[2:3] op_sel_hi:[0,1,1]
	ds_read2_b32 v[4:5], v70 offset1:1
	ds_read2_b32 v[10:11], v85 offset1:1
	v_add_u32_e32 v32, 0x1058, v49
	s_waitcnt lgkmcnt(1)
	v_mov_b32_e32 v12, v4
	s_waitcnt lgkmcnt(0)
	v_mov_b32_e32 v13, v10
	v_pk_fma_f32 v[2:3], v[64:65], v[12:13], v[2:3] op_sel_hi:[0,1,1]
	v_mov_b32_e32 v10, v5
	v_pk_fma_f32 v[12:13], v[46:47], v[10:11], v[2:3] op_sel_hi:[0,1,1]
	v_pk_fma_f32 v[2:3], v[50:51], v[6:7], v[16:17] op_sel_hi:[0,1,1]
	ds_read2_b32 v[4:5], v44 offset1:1
	ds_read2_b32 v[6:7], v45 offset1:1
	v_add_u32_e32 v44, 0x1068, v49
	v_add_u32_e32 v45, 0x7058, v49
	v_add_u32_e32 v50, 0x7068, v49
	s_waitcnt lgkmcnt(1)
	v_mov_b32_e32 v10, v4
	s_waitcnt lgkmcnt(0)
	v_mov_b32_e32 v11, v6
	v_pk_fma_f32 v[2:3], v[48:49], v[10:11], v[2:3] op_sel_hi:[0,1,1]
	v_mov_b32_e32 v6, v5
	v_pk_fma_f32 v[2:3], v[54:55], v[6:7], v[2:3] op_sel_hi:[0,1,1]
	ds_read2_b32 v[4:5], v59 offset1:1
	ds_read2_b32 v[6:7], v61 offset1:1
	s_waitcnt lgkmcnt(1)
	v_mov_b32_e32 v10, v4
	s_waitcnt lgkmcnt(0)
	v_mov_b32_e32 v11, v6
	v_pk_fma_f32 v[2:3], v[52:53], v[10:11], v[2:3] op_sel_hi:[0,1,1]
	v_mov_b32_e32 v6, v5
	v_pk_fma_f32 v[2:3], v[58:59], v[6:7], v[2:3] op_sel_hi:[0,1,1]
	ds_read2_b32 v[4:5], v75 offset1:1
	ds_read2_b32 v[6:7], v76 offset1:1
	s_waitcnt lgkmcnt(1)
	v_mov_b32_e32 v10, v4
	s_waitcnt lgkmcnt(0)
	v_mov_b32_e32 v11, v6
	v_pk_fma_f32 v[2:3], v[56:57], v[10:11], v[2:3] op_sel_hi:[0,1,1]
	v_mov_b32_e32 v6, v5
	v_pk_fma_f32 v[2:3], v[62:63], v[6:7], v[2:3] op_sel_hi:[0,1,1]
	ds_read2_b32 v[4:5], v81 offset1:1
	ds_read2_b32 v[6:7], v82 offset1:1
	s_waitcnt lgkmcnt(1)
	v_mov_b32_e32 v10, v4
	s_waitcnt lgkmcnt(0)
	v_mov_b32_e32 v11, v6
	v_pk_fma_f32 v[2:3], v[60:61], v[10:11], v[2:3] op_sel_hi:[0,1,1]
	v_mov_b32_e32 v6, v5
	v_pk_fma_f32 v[2:3], v[66:67], v[6:7], v[2:3] op_sel_hi:[0,1,1]
	ds_read2_b32 v[4:5], v86 offset1:1
	ds_read2_b32 v[6:7], v87 offset1:1
	s_waitcnt lgkmcnt(1)
	v_mov_b32_e32 v10, v4
	s_waitcnt lgkmcnt(0)
	v_mov_b32_e32 v11, v6
	v_pk_fma_f32 v[2:3], v[64:65], v[10:11], v[2:3] op_sel_hi:[0,1,1]
	v_mov_b32_e32 v6, v5
	v_pk_fma_f32 v[10:11], v[46:47], v[6:7], v[2:3] op_sel_hi:[0,1,1]
	ds_read2_b32 v[2:3], v47 offset1:1
	ds_read2_b32 v[4:5], v51 offset1:1
	v_add_u32_e32 v51, 0x2058, v49
	s_waitcnt lgkmcnt(1)
	v_mov_b32_e32 v6, v2
	s_waitcnt lgkmcnt(0)
	v_mov_b32_e32 v7, v4
	v_pk_fma_f32 v[0:1], v[48:49], v[6:7], v[0:1] op_sel_hi:[0,1,1]
	v_mov_b32_e32 v4, v3
	v_pk_fma_f32 v[0:1], v[54:55], v[4:5], v[0:1] op_sel_hi:[0,1,1]
	ds_read2_b32 v[2:3], v63 offset1:1
	ds_read2_b32 v[4:5], v67 offset1:1
	v_add_u32_e32 v48, 0x6068, v49
	s_waitcnt lgkmcnt(1)
	v_mov_b32_e32 v6, v2
	s_waitcnt lgkmcnt(0)
	v_mov_b32_e32 v7, v4
	v_pk_fma_f32 v[0:1], v[52:53], v[6:7], v[0:1] op_sel_hi:[0,1,1]
	v_mov_b32_e32 v4, v3
	v_pk_fma_f32 v[0:1], v[58:59], v[4:5], v[0:1] op_sel_hi:[0,1,1]
	ds_read2_b32 v[2:3], v77 offset1:1
	ds_read2_b32 v[4:5], v78 offset1:1
	s_waitcnt lgkmcnt(1)
	v_mov_b32_e32 v6, v2
	s_waitcnt lgkmcnt(0)
	v_mov_b32_e32 v7, v4
	v_pk_fma_f32 v[0:1], v[56:57], v[6:7], v[0:1] op_sel_hi:[0,1,1]
	v_mov_b32_e32 v4, v3
	v_pk_fma_f32 v[0:1], v[62:63], v[4:5], v[0:1] op_sel_hi:[0,1,1]
	ds_read2_b32 v[2:3], v83 offset1:1
	ds_read2_b32 v[4:5], v84 offset1:1
	v_add_u32_e32 v63, 0x2068, v49
	v_add_u32_e32 v62, 0x5058, v49
	s_waitcnt lgkmcnt(1)
	v_mov_b32_e32 v6, v2
	s_waitcnt lgkmcnt(0)
	v_mov_b32_e32 v7, v4
	v_pk_fma_f32 v[0:1], v[60:61], v[6:7], v[0:1] op_sel_hi:[0,1,1]
	v_mov_b32_e32 v4, v3
	v_pk_fma_f32 v[0:1], v[66:67], v[4:5], v[0:1] op_sel_hi:[0,1,1]
	ds_read2_b32 v[2:3], v88 offset1:1
	ds_read2_b32 v[4:5], v89 offset1:1
	v_add_u32_e32 v60, 0x3058, v49
	v_add_u32_e32 v61, 0x4058, v49
	v_add_u32_e32 v66, 0x4068, v49
	s_waitcnt lgkmcnt(1)
	v_mov_b32_e32 v6, v2
	s_waitcnt lgkmcnt(0)
	v_mov_b32_e32 v7, v4
	v_pk_fma_f32 v[0:1], v[64:65], v[6:7], v[0:1] op_sel_hi:[0,1,1]
	v_mov_b32_e32 v4, v3
	v_pk_fma_f32 v[4:5], v[46:47], v[4:5], v[0:1] op_sel_hi:[0,1,1]
	ds_read_b32 v18, v49 offset:84
	ds_read_b32 v19, v49 offset:4180
	ds_read_b32 v16, v49 offset:8276
	ds_read_b32 v17, v49 offset:12372
	ds_read_b32 v14, v49 offset:16468
	ds_read_b32 v15, v49 offset:20564
	ds_read_b32 v6, v49 offset:24660
	ds_read_b32 v7, v49 offset:28756
	ds_read_b128 v[0:3], v49 offset:32848
	s_waitcnt vmcnt(10)
	v_mov_b32_e32 v47, v36
	s_waitcnt lgkmcnt(5)
	v_pk_fma_f32 v[12:13], v[36:37], v[16:17], v[12:13] op_sel_hi:[0,1,1]
	v_add_u32_e32 v64, 0x3068, v49
	s_waitcnt lgkmcnt(3)
	v_pk_fma_f32 v[10:11], v[36:37], v[14:15], v[10:11] op_sel_hi:[0,1,1]
	s_waitcnt lgkmcnt(0)
	v_pk_mul_f32 v[0:1], v[46:47], v[0:1]
	s_waitcnt vmcnt(8)
	v_pk_mul_f32 v[2:3], v[34:35], v[2:3]
	v_add_f32_e32 v0, v29, v0
	v_add_f32_e32 v0, v0, v1
	v_add_f32_e32 v0, v0, v2
	v_add_f32_e32 v33, v0, v3
	ds_read_b128 v[0:3], v49 offset:32864
	s_waitcnt vmcnt(2)
	v_mov_b32_e32 v46, v43
	v_add_u32_e32 v29, 0x6058, v49
	v_add_u32_e32 v67, 0x5068, v49
	s_waitcnt lgkmcnt(0)
	v_pk_mul_f32 v[0:1], v[38:39], v[0:1]
	s_nop 0
	v_add_f32_e32 v0, v33, v0
	v_add_f32_e32 v33, v0, v1
	v_pk_mul_f32 v[0:1], v[40:41], v[2:3]
	s_nop 0
	v_add_f32_e32 v0, v33, v0
	v_add_f32_e32 v33, v0, v1
	ds_read_b128 v[0:3], v49 offset:32880
	ds_read2_b64 v[52:55], v49 offset0:11 offset1:12
	ds_read2_b64 v[56:59], v32 offset1:1
	s_waitcnt lgkmcnt(2)
	v_pk_mul_f32 v[0:1], v[42:43], v[0:1]
	s_nop 0
	v_add_f32_e32 v0, v33, v0
	v_add_f32_e32 v47, v0, v1
	v_pk_fma_f32 v[0:1], v[36:37], v[18:19], v[8:9] op_sel_hi:[0,1,1]
	s_waitcnt lgkmcnt(1)
	v_mov_b32_e32 v8, v52
	s_waitcnt lgkmcnt(0)
	v_mov_b32_e32 v9, v56
	v_pk_fma_f32 v[8:9], v[34:35], v[8:9], v[0:1] op_sel_hi:[0,1,1]
	v_mov_b32_e32 v0, v35
	v_mov_b32_e32 v56, v53
	v_pk_fma_f32 v[8:9], v[0:1], v[56:57], v[8:9] op_sel_hi:[0,1,1]
	v_mov_b32_e32 v18, v54
	v_mov_b32_e32 v19, v58
	v_pk_fma_f32 v[8:9], v[38:39], v[18:19], v[8:9] op_sel_hi:[0,1,1]
	v_mov_b32_e32 v18, v39
	v_mov_b32_e32 v58, v55
	v_pk_fma_f32 v[8:9], v[18:19], v[58:59], v[8:9] op_sel_hi:[0,1,1]
	ds_read2_b64 v[52:55], v49 offset0:13 offset1:14
	ds_read2_b64 v[56:59], v44 offset1:1
	v_mov_b32_e32 v44, v41
	s_waitcnt lgkmcnt(1)
	v_mov_b32_e32 v32, v52
	s_waitcnt lgkmcnt(0)
	v_mov_b32_e32 v33, v56
	v_pk_fma_f32 v[8:9], v[40:41], v[32:33], v[8:9] op_sel_hi:[0,1,1]
	v_mov_b32_e32 v56, v53
	v_pk_fma_f32 v[8:9], v[44:45], v[56:57], v[8:9] op_sel_hi:[0,1,1]
	v_mov_b32_e32 v32, v54
	v_mov_b32_e32 v33, v58
	v_pk_fma_f32 v[8:9], v[42:43], v[32:33], v[8:9] op_sel_hi:[0,1,1]
	ds_read_b64 v[32:33], v49 offset:120
	ds_read_b64 v[52:53], v49 offset:4216
	v_mov_b32_e32 v58, v55
	v_pk_fma_f32 v[8:9], v[46:47], v[58:59], v[8:9] op_sel_hi:[0,1,1]
	s_waitcnt lgkmcnt(1)
	v_mov_b32_e32 v54, v32
	s_waitcnt lgkmcnt(0)
	v_mov_b32_e32 v55, v52
	s_waitcnt vmcnt(1)
	v_pk_fma_f32 v[8:9], v[28:29], v[54:55], v[8:9] op_sel_hi:[0,1,1]
	v_mov_b32_e32 v52, v33
	s_waitcnt vmcnt(0)
	v_pk_fma_f32 v[8:9], v[30:31], v[52:53], v[8:9] op_sel_hi:[0,1,1]
	ds_read2_b64 v[52:55], v51 offset1:1
	ds_read2_b64 v[56:59], v60 offset1:1
	s_waitcnt lgkmcnt(1)
	v_mov_b32_e32 v16, v52
	s_waitcnt lgkmcnt(0)
	v_mov_b32_e32 v17, v56
	v_pk_fma_f32 v[12:13], v[34:35], v[16:17], v[12:13] op_sel_hi:[0,1,1]
	v_mov_b32_e32 v56, v53
	v_pk_fma_f32 v[12:13], v[0:1], v[56:57], v[12:13] op_sel_hi:[0,1,1]
	v_mov_b32_e32 v16, v54
	v_mov_b32_e32 v17, v58
	v_pk_fma_f32 v[12:13], v[38:39], v[16:17], v[12:13] op_sel_hi:[0,1,1]
	v_mov_b32_e32 v58, v55
	v_pk_fma_f32 v[12:13], v[18:19], v[58:59], v[12:13] op_sel_hi:[0,1,1]
	ds_read2_b64 v[52:55], v63 offset1:1
	ds_read2_b64 v[56:59], v64 offset1:1
	s_waitcnt lgkmcnt(1)
	v_mov_b32_e32 v16, v52
	s_waitcnt lgkmcnt(0)
	v_mov_b32_e32 v17, v56
	v_pk_fma_f32 v[12:13], v[40:41], v[16:17], v[12:13] op_sel_hi:[0,1,1]
	v_mov_b32_e32 v56, v53
	v_pk_fma_f32 v[12:13], v[44:45], v[56:57], v[12:13] op_sel_hi:[0,1,1]
	v_mov_b32_e32 v16, v54
	v_mov_b32_e32 v17, v58
	v_pk_fma_f32 v[12:13], v[42:43], v[16:17], v[12:13] op_sel_hi:[0,1,1]
	ds_read_b64 v[16:17], v49 offset:8312
	ds_read_b64 v[32:33], v49 offset:12408
	v_mov_b32_e32 v58, v55
	v_pk_fma_f32 v[12:13], v[46:47], v[58:59], v[12:13] op_sel_hi:[0,1,1]
	s_waitcnt lgkmcnt(1)
	v_mov_b32_e32 v52, v16
	s_waitcnt lgkmcnt(0)
	v_mov_b32_e32 v53, v32
	v_pk_fma_f32 v[12:13], v[28:29], v[52:53], v[12:13] op_sel_hi:[0,1,1]
	v_mov_b32_e32 v32, v17
	ds_read2_b64 v[14:17], v61 offset1:1
	ds_read2_b64 v[52:55], v62 offset1:1
	v_pk_fma_f32 v[12:13], v[30:31], v[32:33], v[12:13] op_sel_hi:[0,1,1]
	s_waitcnt lgkmcnt(1)
	v_mov_b32_e32 v32, v14
	s_waitcnt lgkmcnt(0)
	v_mov_b32_e32 v33, v52
	v_pk_fma_f32 v[10:11], v[34:35], v[32:33], v[10:11] op_sel_hi:[0,1,1]
	v_mov_b32_e32 v52, v15
	v_pk_fma_f32 v[10:11], v[0:1], v[52:53], v[10:11] op_sel_hi:[0,1,1]
	v_mov_b32_e32 v14, v16
	v_mov_b32_e32 v15, v54
	v_pk_fma_f32 v[10:11], v[38:39], v[14:15], v[10:11] op_sel_hi:[0,1,1]
	v_mov_b32_e32 v54, v17
	v_pk_fma_f32 v[10:11], v[18:19], v[54:55], v[10:11] op_sel_hi:[0,1,1]
	ds_read2_b64 v[14:17], v66 offset1:1
	ds_read2_b64 v[52:55], v67 offset1:1
	s_waitcnt lgkmcnt(1)
	v_mov_b32_e32 v32, v14
	s_waitcnt lgkmcnt(0)
	v_mov_b32_e32 v33, v52
	v_pk_fma_f32 v[10:11], v[40:41], v[32:33], v[10:11] op_sel_hi:[0,1,1]
	v_mov_b32_e32 v52, v15
	v_pk_fma_f32 v[10:11], v[44:45], v[52:53], v[10:11] op_sel_hi:[0,1,1]
	v_mov_b32_e32 v14, v16
	v_mov_b32_e32 v15, v54
	v_pk_fma_f32 v[10:11], v[42:43], v[14:15], v[10:11] op_sel_hi:[0,1,1]
	v_mov_b32_e32 v54, v17
	ds_read_b64 v[14:15], v49 offset:16504
	ds_read_b64 v[16:17], v49 offset:20600
	v_pk_fma_f32 v[10:11], v[46:47], v[54:55], v[10:11] op_sel_hi:[0,1,1]
	s_waitcnt lgkmcnt(1)
	v_mov_b32_e32 v32, v14
	s_waitcnt lgkmcnt(0)
	v_mov_b32_e32 v33, v16
	v_pk_fma_f32 v[10:11], v[28:29], v[32:33], v[10:11] op_sel_hi:[0,1,1]
	v_mov_b32_e32 v16, v15
	v_pk_fma_f32 v[32:33], v[30:31], v[16:17], v[10:11] op_sel_hi:[0,1,1]
	v_pk_fma_f32 v[10:11], v[36:37], v[6:7], v[4:5] op_sel_hi:[0,1,1]
	ds_read2_b64 v[4:7], v29 offset1:1
	ds_read2_b64 v[14:17], v45 offset1:1
	s_waitcnt lgkmcnt(1)
	v_mov_b32_e32 v52, v4
	s_waitcnt lgkmcnt(0)
	v_mov_b32_e32 v53, v14
	v_pk_fma_f32 v[10:11], v[34:35], v[52:53], v[10:11] op_sel_hi:[0,1,1]
	v_mov_b32_e32 v14, v5
	v_pk_fma_f32 v[0:1], v[0:1], v[14:15], v[10:11] op_sel_hi:[0,1,1]
	v_mov_b32_e32 v4, v6
	v_mov_b32_e32 v5, v16
	v_pk_fma_f32 v[0:1], v[38:39], v[4:5], v[0:1] op_sel_hi:[0,1,1]
	v_mov_b32_e32 v16, v7
	v_pk_fma_f32 v[0:1], v[18:19], v[16:17], v[0:1] op_sel_hi:[0,1,1]
	ds_read2_b64 v[4:7], v48 offset1:1
	ds_read2_b64 v[14:17], v50 offset1:1
	s_waitcnt lgkmcnt(1)
	v_mov_b32_e32 v10, v4
	s_waitcnt lgkmcnt(0)
	v_mov_b32_e32 v11, v14
	v_pk_fma_f32 v[0:1], v[40:41], v[10:11], v[0:1] op_sel_hi:[0,1,1]
	v_mov_b32_e32 v14, v5
	v_pk_fma_f32 v[0:1], v[44:45], v[14:15], v[0:1] op_sel_hi:[0,1,1]
	v_mov_b32_e32 v4, v6
	v_mov_b32_e32 v5, v16
	v_pk_fma_f32 v[0:1], v[42:43], v[4:5], v[0:1] op_sel_hi:[0,1,1]
	v_mov_b32_e32 v16, v7
	ds_read_b64 v[4:5], v49 offset:24696
	ds_read_b64 v[6:7], v49 offset:28792
	v_pk_fma_f32 v[0:1], v[46:47], v[16:17], v[0:1] op_sel_hi:[0,1,1]
	v_add_u32_e32 v49, 0x80, v49
	s_waitcnt lgkmcnt(1)
	v_mov_b32_e32 v10, v4
	s_waitcnt lgkmcnt(0)
	v_mov_b32_e32 v11, v6
	v_pk_fma_f32 v[0:1], v[28:29], v[10:11], v[0:1] op_sel_hi:[0,1,1]
	v_mov_b32_e32 v6, v5
	v_mov_b32_e32 v29, v30
	v_pk_fma_f32 v[44:45], v[30:31], v[6:7], v[0:1] op_sel_hi:[0,1,1]
	v_pk_mul_f32 v[0:1], v[28:29], v[2:3]
	s_nop 0
	v_add_f32_e32 v0, v47, v0
	v_add_f32_e32 v29, v0, v1
	s_cbranch_scc0 .LBB0_1986
	v_lshl_add_u32 v0, v31, 2, 0
	s_movk_i32 s0, 0x900
	v_mad_u64_u32 v[2:3], s[0:1], v37, s0, v[0:1]
	s_movk_i32 s0, 0x240
	s_nop 0
	v_cmp_gt_i32_e32 vcc, s0, v20
	ds_write2st64_b32 v2, v8, v9 offset0:144 offset1:145
	ds_write2st64_b32 v2, v12, v13 offset0:146 offset1:147
	ds_write2st64_b32 v2, v32, v33 offset0:148 offset1:149
	ds_write2st64_b32 v2, v44, v45 offset0:150 offset1:151
	ds_write_b32 v2, v29 offset:38912
	s_waitcnt lgkmcnt(0)
	s_barrier
	s_and_saveexec_b64 s[6:7], vcc
	s_cbranch_execz .LBB0_1995
	v_max_i32_e32 v1, 64, v20
	s_add_i32 s0, s66, 0xfffff500
	v_sub_u32_e32 v1, v1, v20
	v_or_b32_e32 v64, s0, v31
	v_add_u32_e32 v1, 0x1ff, v1
	s_movk_i32 s0, 0x1ff
	v_lshl_add_u64 v[2:3], v[64:65], 2, s[22:23]
	v_cmp_lt_u32_e32 vcc, s0, v1
	s_mov_b64 s[56:57], -1
	s_and_saveexec_b64 s[34:35], vcc
	s_cbranch_execz .LBB0_1992
	v_lshrrev_b32_e32 v1, 9, v1
	v_add_u32_e32 v1, 1, v1
	v_and_b32_e32 v6, 0xfffffe, v1
	s_mov_b64 s[56:57], 0
	v_mov_b32_e32 v7, v6
	v_mov_b64_e32 v[4:5], v[20:21]

.LBB0_1996:
	s_and_b64 vcc, exec, s[6:7]
	s_cbranch_vccz .LBB0_1911
	v_mov_b32_e32 v20, v228
	s_waitcnt lgkmcnt(0)
	v_and_b32_e32 v0, 0x3ff, v20
	v_cmp_lt_u32_e32 vcc, s92, v20
	v_lshlrev_b32_e32 v64, 2, v0
	s_barrier
	s_and_saveexec_b64 s[0:1], vcc
	s_xor_b64 s[6:7], exec, s[0:1]
	v_ashrrev_i32_e32 v0, 10, v20
	v_add_u32_e32 v0, -1, v0
	v_mul_hi_i32_i24_e32 v1, 0x6000, v0
	v_mul_i32_i24_e32 v0, 0x6000, v0
	v_lshl_add_u64 v[0:1], s[24:25], 0, v[0:1]
	v_lshl_add_u64 v[0:1], v[0:1], 0, v[64:65]
	s_andn2_saveexec_b64 s[6:7], s[6:7]
	v_lshl_add_u64 v[0:1], s[16:17], 0, v[64:65]
	s_or_b64 exec, exec, s[6:7]
	global_load_dword v4, v[0:1], off nt
	v_add_u32_e32 v21, 0x200, v20
	v_and_b32_e32 v0, 0x3ff, v21
	v_cmp_lt_u32_e32 vcc, s92, v21
	v_lshlrev_b32_e32 v0, 2, v0
	s_and_saveexec_b64 s[0:1], vcc
	s_xor_b64 s[6:7], exec, s[0:1]
	v_ashrrev_i32_e32 v1, 10, v21
	v_add_u32_e32 v1, -1, v1
	v_mul_hi_i32_i24_e32 v3, 0x6000, v1
	v_mul_i32_i24_e32 v2, 0x6000, v1
	v_lshl_add_u64 v[2:3], s[24:25], 0, v[2:3]
	v_mov_b32_e32 v1, v65
	v_lshl_add_u64 v[2:3], v[2:3], 0, v[0:1]
	s_andn2_saveexec_b64 s[6:7], s[6:7]
	v_mov_b32_e32 v1, v65
	v_lshl_add_u64 v[2:3], s[16:17], 0, v[0:1]
	s_or_b64 exec, exec, s[6:7]
	global_load_dword v5, v[2:3], off nt
	s_movk_i32 s0, 0xfc00
	v_cmp_gt_u32_e32 vcc, s0, v20
	s_and_saveexec_b64 s[0:1], vcc
	s_xor_b64 s[6:7], exec, s[0:1]
	v_add_u32_e32 v0, 0x400, v20
	v_ashrrev_i32_e32 v0, 10, v0
	v_add_u32_e32 v0, -1, v0
	v_mul_hi_i32_i24_e32 v1, 0x6000, v0
	v_mul_i32_i24_e32 v0, 0x6000, v0
	v_lshl_add_u64 v[0:1], s[24:25], 0, v[0:1]
	v_lshl_add_u64 v[0:1], v[0:1], 0, v[64:65]
	s_andn2_saveexec_b64 s[6:7], s[6:7]
	v_lshl_add_u64 v[0:1], s[16:17], 0, v[64:65]
	s_or_b64 exec, exec, s[6:7]
	global_load_dword v6, v[0:1], off nt
	v_add_u32_e32 v1, 0x600, v20
	v_and_b32_e32 v0, 0x3ff, v1
	v_cmp_lt_u32_e32 vcc, s92, v1
	v_lshlrev_b32_e32 v0, 2, v0
	s_and_saveexec_b64 s[0:1], vcc
	s_xor_b64 s[6:7], exec, s[0:1]
	v_ashrrev_i32_e32 v1, 10, v1
	v_add_u32_e32 v1, -1, v1
	v_mul_hi_i32_i24_e32 v3, 0x6000, v1
	v_mul_i32_i24_e32 v2, 0x6000, v1
	v_lshl_add_u64 v[2:3], s[24:25], 0, v[2:3]
	v_mov_b32_e32 v1, v65
	v_lshl_add_u64 v[2:3], v[2:3], 0, v[0:1]
	s_andn2_saveexec_b64 s[6:7], s[6:7]
	v_mov_b32_e32 v1, v65
	v_lshl_add_u64 v[2:3], s[16:17], 0, v[0:1]
	s_or_b64 exec, exec, s[6:7]
	global_load_dword v7, v[2:3], off nt
	v_add_u32_e32 v2, 0x800, v20
	v_cmp_lt_u32_e32 vcc, s92, v2
	s_and_saveexec_b64 s[0:1], vcc
	s_xor_b64 s[6:7], exec, s[0:1]
	v_ashrrev_i32_e32 v0, 10, v2
	v_add_u32_e32 v0, -1, v0
	v_mul_hi_i32_i24_e32 v1, 0x6000, v0
	v_mul_i32_i24_e32 v0, 0x6000, v0
	v_lshl_add_u64 v[0:1], s[24:25], 0, v[0:1]
	v_lshl_add_u64 v[0:1], v[0:1], 0, v[64:65]
	s_andn2_saveexec_b64 s[6:7], s[6:7]
	v_lshl_add_u64 v[0:1], s[16:17], 0, v[64:65]
	s_or_b64 exec, exec, s[6:7]
	global_load_dword v8, v[0:1], off nt
	v_add_u32_e32 v1, 0xa00, v20
	v_and_b32_e32 v0, 0x3ff, v1
	v_cmp_lt_u32_e32 vcc, s92, v1
	v_lshlrev_b32_e32 v0, 2, v0
	s_and_saveexec_b64 s[0:1], vcc
	s_xor_b64 s[6:7], exec, s[0:1]
	v_ashrrev_i32_e32 v1, 10, v1
	v_add_u32_e32 v1, -1, v1
	v_mul_hi_i32_i24_e32 v3, 0x6000, v1
	v_mul_i32_i24_e32 v2, 0x6000, v1
	v_lshl_add_u64 v[2:3], s[24:25], 0, v[2:3]
	v_mov_b32_e32 v1, v65
	v_lshl_add_u64 v[2:3], v[2:3], 0, v[0:1]
	s_andn2_saveexec_b64 s[6:7], s[6:7]
	v_mov_b32_e32 v1, v65
	v_lshl_add_u64 v[2:3], s[16:17], 0, v[0:1]
	s_or_b64 exec, exec, s[6:7]
	global_load_dword v9, v[2:3], off nt
	v_add_u32_e32 v2, 0xc00, v20
	v_cmp_lt_u32_e32 vcc, s92, v2
	s_and_saveexec_b64 s[0:1], vcc
	s_xor_b64 s[6:7], exec, s[0:1]
	v_ashrrev_i32_e32 v0, 10, v2
	v_add_u32_e32 v0, -1, v0
	v_mul_hi_i32_i24_e32 v1, 0x6000, v0
	v_mul_i32_i24_e32 v0, 0x6000, v0
	v_lshl_add_u64 v[0:1], s[24:25], 0, v[0:1]
	v_lshl_add_u64 v[0:1], v[0:1], 0, v[64:65]
	s_andn2_saveexec_b64 s[6:7], s[6:7]
	v_lshl_add_u64 v[0:1], s[16:17], 0, v[64:65]
	s_or_b64 exec, exec, s[6:7]
	global_load_dword v10, v[0:1], off nt
	v_add_u32_e32 v1, 0xe00, v20
	v_and_b32_e32 v0, 0x3ff, v1
	v_cmp_lt_u32_e32 vcc, s92, v1
	v_lshlrev_b32_e32 v0, 2, v0
	s_and_saveexec_b64 s[0:1], vcc
	s_xor_b64 s[6:7], exec, s[0:1]
	v_ashrrev_i32_e32 v1, 10, v1
	v_add_u32_e32 v1, -1, v1
	v_mul_hi_i32_i24_e32 v3, 0x6000, v1
	v_mul_i32_i24_e32 v2, 0x6000, v1
	v_lshl_add_u64 v[2:3], s[24:25], 0, v[2:3]
	v_mov_b32_e32 v1, v65
	v_lshl_add_u64 v[2:3], v[2:3], 0, v[0:1]
	s_andn2_saveexec_b64 s[6:7], s[6:7]
	v_mov_b32_e32 v1, v65
	v_lshl_add_u64 v[2:3], s[16:17], 0, v[0:1]
	s_or_b64 exec, exec, s[6:7]
	global_load_dword v11, v[2:3], off nt
	v_add_u32_e32 v2, 0x1000, v20
	v_cmp_lt_u32_e32 vcc, s92, v2
	s_and_saveexec_b64 s[0:1], vcc
	s_xor_b64 s[6:7], exec, s[0:1]
	v_ashrrev_i32_e32 v0, 10, v2
	v_add_u32_e32 v0, -1, v0
	v_mul_hi_i32_i24_e32 v1, 0x6000, v0
	v_mul_i32_i24_e32 v0, 0x6000, v0
	v_lshl_add_u64 v[0:1], s[24:25], 0, v[0:1]
	v_lshl_add_u64 v[0:1], v[0:1], 0, v[64:65]
	s_andn2_saveexec_b64 s[6:7], s[6:7]
	v_lshl_add_u64 v[0:1], s[16:17], 0, v[64:65]
	s_or_b64 exec, exec, s[6:7]
	global_load_dword v12, v[0:1], off nt
	v_add_u32_e32 v1, 0x1200, v20
	v_and_b32_e32 v0, 0x3ff, v1
	v_cmp_lt_u32_e32 vcc, s92, v1
	v_lshlrev_b32_e32 v0, 2, v0
	s_and_saveexec_b64 s[0:1], vcc
	s_xor_b64 s[6:7], exec, s[0:1]
	v_ashrrev_i32_e32 v1, 10, v1
	v_add_u32_e32 v1, -1, v1
	v_mul_hi_i32_i24_e32 v3, 0x6000, v1
	v_mul_i32_i24_e32 v2, 0x6000, v1
	v_lshl_add_u64 v[2:3], s[24:25], 0, v[2:3]
	v_mov_b32_e32 v1, v65
	v_lshl_add_u64 v[2:3], v[2:3], 0, v[0:1]
	s_andn2_saveexec_b64 s[6:7], s[6:7]
	v_mov_b32_e32 v1, v65
	v_lshl_add_u64 v[2:3], s[16:17], 0, v[0:1]
	s_or_b64 exec, exec, s[6:7]
	global_load_dword v13, v[2:3], off nt
	v_add_u32_e32 v2, 0x1400, v20
	v_cmp_lt_u32_e32 vcc, s92, v2
	s_and_saveexec_b64 s[0:1], vcc
	s_xor_b64 s[6:7], exec, s[0:1]
	v_ashrrev_i32_e32 v0, 10, v2
	v_add_u32_e32 v0, -1, v0
	v_mul_hi_i32_i24_e32 v1, 0x6000, v0
	v_mul_i32_i24_e32 v0, 0x6000, v0
	v_lshl_add_u64 v[0:1], s[24:25], 0, v[0:1]
	v_lshl_add_u64 v[0:1], v[0:1], 0, v[64:65]
	s_andn2_saveexec_b64 s[6:7], s[6:7]
	v_lshl_add_u64 v[0:1], s[16:17], 0, v[64:65]
	s_or_b64 exec, exec, s[6:7]
	global_load_dword v14, v[0:1], off nt
	v_add_u32_e32 v1, 0x1600, v20
	v_and_b32_e32 v0, 0x3ff, v1
	v_cmp_lt_u32_e32 vcc, s92, v1
	v_lshlrev_b32_e32 v0, 2, v0
	s_and_saveexec_b64 s[0:1], vcc
	s_xor_b64 s[6:7], exec, s[0:1]
	v_ashrrev_i32_e32 v1, 10, v1
	v_add_u32_e32 v1, -1, v1
	v_mul_hi_i32_i24_e32 v3, 0x6000, v1
	v_mul_i32_i24_e32 v2, 0x6000, v1
	v_lshl_add_u64 v[2:3], s[24:25], 0, v[2:3]
	v_mov_b32_e32 v1, v65
	v_lshl_add_u64 v[2:3], v[2:3], 0, v[0:1]
	s_andn2_saveexec_b64 s[6:7], s[6:7]
	v_mov_b32_e32 v1, v65
	v_lshl_add_u64 v[2:3], s[16:17], 0, v[0:1]
	s_or_b64 exec, exec, s[6:7]
	global_load_dword v15, v[2:3], off nt
	v_add_u32_e32 v2, 0x1800, v20
	v_cmp_lt_u32_e32 vcc, s92, v2
	s_and_saveexec_b64 s[0:1], vcc
	s_xor_b64 s[6:7], exec, s[0:1]
	v_ashrrev_i32_e32 v0, 10, v2
	v_add_u32_e32 v0, -1, v0
	v_mul_hi_i32_i24_e32 v1, 0x6000, v0
	v_mul_i32_i24_e32 v0, 0x6000, v0
	v_lshl_add_u64 v[0:1], s[24:25], 0, v[0:1]
	v_lshl_add_u64 v[0:1], v[0:1], 0, v[64:65]
	s_andn2_saveexec_b64 s[6:7], s[6:7]
	v_lshl_add_u64 v[0:1], s[16:17], 0, v[64:65]
	s_or_b64 exec, exec, s[6:7]
	global_load_dword v16, v[0:1], off nt
	v_add_u32_e32 v1, 0x1a00, v20
	v_and_b32_e32 v0, 0x3ff, v1
	v_cmp_lt_u32_e32 vcc, s92, v1
	v_lshlrev_b32_e32 v0, 2, v0
	s_and_saveexec_b64 s[0:1], vcc
	s_xor_b64 s[6:7], exec, s[0:1]
	v_ashrrev_i32_e32 v1, 10, v1
	v_add_u32_e32 v1, -1, v1
	v_mul_hi_i32_i24_e32 v3, 0x6000, v1
	v_mul_i32_i24_e32 v2, 0x6000, v1
	v_lshl_add_u64 v[2:3], s[24:25], 0, v[2:3]
	v_mov_b32_e32 v1, v65
	v_lshl_add_u64 v[2:3], v[2:3], 0, v[0:1]
	s_andn2_saveexec_b64 s[6:7], s[6:7]
	v_mov_b32_e32 v1, v65
	v_lshl_add_u64 v[2:3], s[16:17], 0, v[0:1]
	s_or_b64 exec, exec, s[6:7]
	global_load_dword v17, v[2:3], off nt
	v_add_u32_e32 v2, 0x1c00, v20
	v_cmp_lt_u32_e32 vcc, s92, v2
	s_and_saveexec_b64 s[0:1], vcc
	s_xor_b64 s[6:7], exec, s[0:1]
	v_ashrrev_i32_e32 v0, 10, v2
	v_add_u32_e32 v0, -1, v0
	v_mul_hi_i32_i24_e32 v1, 0x6000, v0
	v_mul_i32_i24_e32 v0, 0x6000, v0
	v_lshl_add_u64 v[0:1], s[24:25], 0, v[0:1]
	v_lshl_add_u64 v[0:1], v[0:1], 0, v[64:65]
	s_andn2_saveexec_b64 s[6:7], s[6:7]
	v_lshl_add_u64 v[0:1], s[16:17], 0, v[64:65]
	s_or_b64 exec, exec, s[6:7]
	global_load_dword v18, v[0:1], off nt
	v_add_u32_e32 v1, 0x1e00, v20
	v_and_b32_e32 v0, 0x3ff, v1
	v_cmp_lt_u32_e32 vcc, s92, v1
	v_lshlrev_b32_e32 v0, 2, v0
	s_and_saveexec_b64 s[0:1], vcc
	s_xor_b64 s[6:7], exec, s[0:1]
	v_ashrrev_i32_e32 v1, 10, v1
	v_add_u32_e32 v1, -1, v1
	v_mul_hi_i32_i24_e32 v3, 0x6000, v1
	v_mul_i32_i24_e32 v2, 0x6000, v1
	v_lshl_add_u64 v[2:3], s[24:25], 0, v[2:3]
	v_mov_b32_e32 v1, v65
	v_lshl_add_u64 v[2:3], v[2:3], 0, v[0:1]
	s_andn2_saveexec_b64 s[6:7], s[6:7]
	v_mov_b32_e32 v1, v65
	v_lshl_add_u64 v[2:3], s[16:17], 0, v[0:1]
	s_or_b64 exec, exec, s[6:7]
	global_load_dword v2, v[2:3], off nt
	v_add_u32_e32 v3, 0x2000, v20
	v_cmp_lt_u32_e32 vcc, s92, v3
	s_and_saveexec_b64 s[0:1], vcc
	s_xor_b64 s[6:7], exec, s[0:1]
	v_ashrrev_i32_e32 v0, 10, v3
	v_add_u32_e32 v0, -1, v0
	v_mul_hi_i32_i24_e32 v1, 0x6000, v0
	v_mul_i32_i24_e32 v0, 0x6000, v0
	v_lshl_add_u64 v[0:1], s[24:25], 0, v[0:1]
	v_lshl_add_u64 v[0:1], v[0:1], 0, v[64:65]
	s_andn2_saveexec_b64 s[6:7], s[6:7]
	v_lshl_add_u64 v[0:1], s[16:17], 0, v[64:65]
	s_or_b64 exec, exec, s[6:7]
	global_load_dword v3, v[0:1], off nt
	v_add_u32_e32 v19, 0x2200, v20
	v_and_b32_e32 v0, 0x3ff, v19
	v_cmp_lt_u32_e32 vcc, s92, v19
	v_lshlrev_b32_e32 v64, 2, v0
	s_and_saveexec_b64 s[0:1], vcc
	s_xor_b64 s[6:7], exec, s[0:1]
	v_ashrrev_i32_e32 v0, 10, v19
	v_add_u32_e32 v0, -1, v0
	v_mul_hi_i32_i24_e32 v1, 0x6000, v0
	v_mul_i32_i24_e32 v0, 0x6000, v0
	v_lshl_add_u64 v[0:1], s[24:25], 0, v[0:1]
	v_lshl_add_u64 v[0:1], v[0:1], 0, v[64:65]
	s_andn2_saveexec_b64 s[6:7], s[6:7]
	v_lshl_add_u64 v[0:1], s[16:17], 0, v[64:65]
	s_or_b64 exec, exec, s[6:7]
	global_load_dword v0, v[0:1], off nt
	v_lshl_add_u32 v1, v20, 2, 0
	v_ashrrev_i32_e32 v37, 6, v20
	v_and_b32_e32 v31, 63, v20
	s_ashr_i32 s83, s82, 31
	v_lshlrev_b32_e32 v64, 2, v31
	v_lshl_add_u32 v49, v37, 9, 0
	s_movk_i32 s4, 0xffe0
	s_waitcnt vmcnt(0)
	ds_write2st64_b32 v1, v4, v5 offset1:8
	ds_write2st64_b32 v1, v6, v7 offset0:16 offset1:24
	ds_write2st64_b32 v1, v8, v9 offset0:32 offset1:40
	ds_write2st64_b32 v1, v10, v11 offset0:48 offset1:56
	ds_write2st64_b32 v1, v12, v13 offset0:64 offset1:72
	ds_write2st64_b32 v1, v14, v15 offset0:80 offset1:88
	ds_write2st64_b32 v1, v16, v17 offset0:96 offset1:104
	ds_write2st64_b32 v1, v18, v2 offset0:112 offset1:120
	ds_write2st64_b32 v1, v3, v0 offset0:128 offset1:136
	v_lshlrev_b32_e32 v2, 7, v37
	v_mov_b64_e32 v[0:1], s[28:29]
	v_mad_i64_i32 v[22:23], s[0:1], v2, s78, v[0:1]
	v_readlane_b32 s0, v255, 15
	v_lshl_add_u64 v[0:1], s[82:83], 2, v[64:65]
	v_readlane_b32 s1, v255, 16
	v_mov_b32_e32 v8, 0
	v_mov_b32_e32 v9, v8
	v_lshl_add_u64 v[24:25], s[0:1], 0, v[0:1]
	v_readlane_b32 s0, v254, 0
	v_readlane_b32 s1, v254, 1
	v_mov_b32_e32 v12, v8
	v_mov_b32_e32 v13, v8
	v_lshl_add_u64 v[26:27], s[0:1], 0, v[0:1]
	v_mov_b32_e32 v32, v8
	v_mov_b32_e32 v33, v8
	v_mov_b32_e32 v44, v8
	v_mov_b32_e32 v45, v8
	v_mov_b32_e32 v29, v8
	s_waitcnt lgkmcnt(0)
	s_barrier
.LBB0_2070:
	v_lshl_add_u64 v[0:1], v[24:25], 0, v[22:23]
	global_load_dword v80, v[0:1], off nt
	v_lshl_add_u64 v[0:1], v[26:27], 0, v[22:23]
	v_add_co_u32_e32 v2, vcc, 0xb02000, v0
	v_add_u32_e32 v51, 0x702c, v49
	s_nop 0
	v_addc_co_u32_e32 v3, vcc, 0, v1, vcc
	global_load_dword v82, v[2:3], off offset:3072 nt
	v_add_co_u32_e32 v2, vcc, 0xb05000, v0
	v_add_u32_e32 v55, 0x2034, v49
	s_nop 0
	v_addc_co_u32_e32 v3, vcc, 0, v1, vcc
	global_load_dword v84, v[2:3], off offset:2048 nt
	v_add_co_u32_e32 v2, vcc, 0xb08000, v0
	v_add_u32_e32 v53, 0x1034, v49
	s_nop 0
	v_addc_co_u32_e32 v3, vcc, 0, v1, vcc
	global_load_dword v86, v[2:3], off offset:1024 nt
	v_add_co_u32_e32 v2, vcc, 0xb0b000, v0
	v_add_u32_e32 v59, 0x4034, v49
	s_nop 0
	v_addc_co_u32_e32 v3, vcc, 0, v1, vcc
	global_load_dword v68, v[2:3], off nt
	v_add_co_u32_e32 v2, vcc, 0xb0d000, v0
	v_add_u32_e32 v57, 0x3034, v49
	s_nop 0
	v_addc_co_u32_e32 v3, vcc, 0, v1, vcc
	global_load_dword v70, v[2:3], off offset:3072 nt
	v_add_co_u32_e32 v2, vcc, 0xb10000, v0
	v_add_u32_e32 v63, 0x6034, v49
	s_nop 0
	v_addc_co_u32_e32 v3, vcc, 0, v1, vcc
	global_load_dword v72, v[2:3], off offset:2048 nt
	v_add_co_u32_e32 v2, vcc, 0xb13000, v0
	v_add_u32_e32 v61, 0x5034, v49
	s_nop 0
	v_addc_co_u32_e32 v3, vcc, 0, v1, vcc
	global_load_dword v76, v[2:3], off offset:1024 nt
	v_add_co_u32_e32 v2, vcc, 0xb16000, v0
	v_add_u32_e32 v67, 0x7034, v49
	s_nop 0
	v_addc_co_u32_e32 v3, vcc, 0, v1, vcc
	global_load_dword v74, v[2:3], off nt
	v_add_co_u32_e32 v2, vcc, 0xb18000, v0
	v_add_u32_e32 v47, 0x602c, v49
	s_nop 0
	v_addc_co_u32_e32 v3, vcc, 0, v1, vcc
	global_load_dword v78, v[2:3], off offset:3072 nt
	v_add_co_u32_e32 v2, vcc, 0xb1b000, v0
	s_add_i32 s4, s4, 32
	s_nop 0
	v_addc_co_u32_e32 v3, vcc, 0, v1, vcc
	global_load_dword v50, v[2:3], off offset:2048 nt
	v_add_co_u32_e32 v2, vcc, 0xb1e000, v0
	s_mov_b64 s[0:1], 0x58000
	s_nop 0
	v_addc_co_u32_e32 v3, vcc, 0, v1, vcc
	global_load_dword v48, v[2:3], off offset:1024 nt
	v_add_co_u32_e32 v2, vcc, 0xb21000, v0
	v_lshl_add_u64 v[22:23], v[22:23], 0, s[0:1]
	s_nop 0
	v_addc_co_u32_e32 v3, vcc, 0, v1, vcc
	global_load_dword v54, v[2:3], off nt
	v_add_co_u32_e32 v2, vcc, 0xb23000, v0
	s_cmpk_gt_u32 s4, 0x5f
	s_nop 0
	v_addc_co_u32_e32 v3, vcc, 0, v1, vcc
	global_load_dword v52, v[2:3], off offset:3072 nt
	v_add_co_u32_e32 v2, vcc, 0xb26000, v0
	s_nop 1
	v_addc_co_u32_e32 v3, vcc, 0, v1, vcc
	global_load_dword v58, v[2:3], off offset:2048 nt
	v_add_co_u32_e32 v2, vcc, 0xb29000, v0
	s_nop 1
	v_addc_co_u32_e32 v3, vcc, 0, v1, vcc
	global_load_dword v56, v[2:3], off offset:1024 nt
	v_add_co_u32_e32 v2, vcc, 0xb2c000, v0
	s_nop 1
	v_addc_co_u32_e32 v3, vcc, 0, v1, vcc
	global_load_dword v62, v[2:3], off nt
	v_add_co_u32_e32 v2, vcc, 0xb2e000, v0
	s_nop 1
	v_addc_co_u32_e32 v3, vcc, 0, v1, vcc
	global_load_dword v60, v[2:3], off offset:3072 nt
	v_add_co_u32_e32 v2, vcc, 0xb31000, v0
	s_nop 1
	v_addc_co_u32_e32 v3, vcc, 0, v1, vcc
	global_load_dword v66, v[2:3], off offset:2048 nt
	v_add_co_u32_e32 v2, vcc, 0xb34000, v0
	s_nop 1
	v_addc_co_u32_e32 v3, vcc, 0, v1, vcc
	global_load_dword v64, v[2:3], off offset:1024 nt
	v_add_co_u32_e32 v2, vcc, 0xb37000, v0
	s_nop 1
	v_addc_co_u32_e32 v3, vcc, 0, v1, vcc
	global_load_dword v46, v[2:3], off nt
	v_add_co_u32_e32 v2, vcc, 0xb39000, v0
	s_nop 1
	v_addc_co_u32_e32 v3, vcc, 0, v1, vcc
	global_load_dword v36, v[2:3], off offset:3072 nt
	v_add_co_u32_e32 v2, vcc, 0xb3c000, v0
	s_nop 1
	v_addc_co_u32_e32 v3, vcc, 0, v1, vcc
	global_load_dword v34, v[2:3], off offset:2048 nt
	v_add_co_u32_e32 v2, vcc, 0xb3f000, v0
	s_nop 1
	v_addc_co_u32_e32 v3, vcc, 0, v1, vcc
	global_load_dword v35, v[2:3], off offset:1024 nt
	v_add_co_u32_e32 v2, vcc, 0xb42000, v0
	s_nop 1
	v_addc_co_u32_e32 v3, vcc, 0, v1, vcc
	global_load_dword v38, v[2:3], off nt
	v_add_co_u32_e32 v2, vcc, 0xb44000, v0
	s_nop 1
	v_addc_co_u32_e32 v3, vcc, 0, v1, vcc
	global_load_dword v39, v[2:3], off offset:3072 nt
	v_add_co_u32_e32 v2, vcc, 0xb47000, v0
	s_nop 1
	v_addc_co_u32_e32 v3, vcc, 0, v1, vcc
	global_load_dword v40, v[2:3], off offset:2048 nt
	v_add_co_u32_e32 v2, vcc, 0xb4a000, v0
	s_nop 1
	v_addc_co_u32_e32 v3, vcc, 0, v1, vcc
	global_load_dword v41, v[2:3], off offset:1024 nt
	v_add_co_u32_e32 v2, vcc, 0xb4d000, v0
	s_nop 1
	v_addc_co_u32_e32 v3, vcc, 0, v1, vcc
	global_load_dword v42, v[2:3], off nt
	v_add_co_u32_e32 v2, vcc, 0xb4f000, v0
	s_nop 1
	v_addc_co_u32_e32 v3, vcc, 0, v1, vcc
	global_load_dword v43, v[2:3], off offset:3072 nt
	v_add_co_u32_e32 v2, vcc, 0xb52000, v0
	s_nop 1
	v_addc_co_u32_e32 v3, vcc, 0, v1, vcc
	v_add_co_u32_e32 v0, vcc, 0xb55000, v0
	global_load_dword v28, v[2:3], off offset:2048 nt
	s_nop 0
	v_addc_co_u32_e32 v1, vcc, 0, v1, vcc
	global_load_dword v30, v[0:1], off offset:1024 nt
	ds_read_b128 v[0:3], v49 offset:32768
	s_waitcnt vmcnt(31) lgkmcnt(0)
	v_fmac_f32_e32 v29, v80, v0
	s_waitcnt vmcnt(30)
	v_fmac_f32_e32 v29, v82, v1
	s_waitcnt vmcnt(29)
	v_fmac_f32_e32 v29, v84, v2
	s_waitcnt vmcnt(28)
	v_fmac_f32_e32 v29, v86, v3
	ds_read_b128 v[0:3], v49 offset:32784
	s_waitcnt vmcnt(27) lgkmcnt(0)
	v_fmac_f32_e32 v29, v68, v0
	s_waitcnt vmcnt(26)
	v_fmac_f32_e32 v29, v70, v1
	s_waitcnt vmcnt(25)
	v_fmac_f32_e32 v29, v72, v2
	s_waitcnt vmcnt(24)
	v_fmac_f32_e32 v29, v76, v3
	ds_read_b128 v[0:3], v49 offset:32800
	ds_read_b128 v[14:17], v49
	ds_read_b128 v[88:91], v49 offset:16
	ds_read_b96 v[4:6], v49 offset:32
	ds_read_b128 v[92:95], v49 offset:4096
	s_waitcnt lgkmcnt(3)
	v_mov_b32_e32 v10, v14
	s_waitcnt vmcnt(23)
	v_fmac_f32_e32 v29, v74, v0
	s_waitcnt lgkmcnt(0)
	v_mov_b32_e32 v11, v92
	v_pk_fma_f32 v[8:9], v[80:81], v[10:11], v[8:9] op_sel_hi:[0,1,1]
	v_mov_b32_e32 v92, v15
	v_pk_fma_f32 v[8:9], v[82:83], v[92:93], v[8:9] op_sel_hi:[0,1,1]
	v_mov_b32_e32 v10, v16
	v_mov_b32_e32 v11, v94
	v_pk_fma_f32 v[8:9], v[84:85], v[10:11], v[8:9] op_sel_hi:[0,1,1]
	v_mov_b32_e32 v94, v17
	v_pk_fma_f32 v[14:15], v[86:87], v[94:95], v[8:9] op_sel_hi:[0,1,1]
	ds_read_b128 v[8:11], v49 offset:4112
	v_mov_b32_e32 v16, v88
	s_waitcnt vmcnt(22)
	v_fmac_f32_e32 v29, v78, v1
	s_waitcnt vmcnt(21)
	v_fmac_f32_e32 v29, v50, v2
	s_waitcnt vmcnt(20)
	v_fmac_f32_e32 v29, v48, v3
	s_waitcnt lgkmcnt(0)
	v_mov_b32_e32 v17, v8
	v_pk_fma_f32 v[14:15], v[68:69], v[16:17], v[14:15] op_sel_hi:[0,1,1]
	v_mov_b32_e32 v8, v89
	v_pk_fma_f32 v[8:9], v[70:71], v[8:9], v[14:15] op_sel_hi:[0,1,1]
	v_mov_b32_e32 v14, v90
	v_mov_b32_e32 v15, v10
	v_pk_fma_f32 v[8:9], v[72:73], v[14:15], v[8:9] op_sel_hi:[0,1,1]
	v_mov_b32_e32 v10, v91
	v_pk_fma_f32 v[14:15], v[76:77], v[10:11], v[8:9] op_sel_hi:[0,1,1]
	ds_read_b96 v[8:10], v49 offset:4128
	v_mov_b32_e32 v16, v4
	s_waitcnt lgkmcnt(0)
	v_mov_b32_e32 v17, v8
	v_pk_fma_f32 v[14:15], v[74:75], v[16:17], v[14:15] op_sel_hi:[0,1,1]
	v_mov_b32_e32 v8, v5
	v_pk_fma_f32 v[4:5], v[78:79], v[8:9], v[14:15] op_sel_hi:[0,1,1]
	ds_read_b128 v[14:17], v49 offset:8192
	ds_read_b128 v[88:91], v49 offset:12288
	s_waitcnt lgkmcnt(1)
	v_mov_b32_e32 v8, v14
	s_waitcnt lgkmcnt(0)
	v_mov_b32_e32 v9, v88
	v_pk_fma_f32 v[8:9], v[80:81], v[8:9], v[12:13] op_sel_hi:[0,1,1]
	v_mov_b32_e32 v88, v15
	v_pk_fma_f32 v[8:9], v[82:83], v[88:89], v[8:9] op_sel_hi:[0,1,1]
	v_mov_b32_e32 v12, v16
	v_mov_b32_e32 v13, v90
	v_pk_fma_f32 v[8:9], v[84:85], v[12:13], v[8:9] op_sel_hi:[0,1,1]
	v_mov_b32_e32 v90, v17
	ds_read_b128 v[12:15], v49 offset:8208
	ds_read_b128 v[16:19], v49 offset:12304
	v_pk_fma_f32 v[8:9], v[86:87], v[90:91], v[8:9] op_sel_hi:[0,1,1]
	s_waitcnt lgkmcnt(1)
	v_mov_b32_e32 v88, v12
	s_waitcnt lgkmcnt(0)
	v_mov_b32_e32 v89, v16
	v_pk_fma_f32 v[8:9], v[68:69], v[88:89], v[8:9] op_sel_hi:[0,1,1]
	v_mov_b32_e32 v16, v13
	v_pk_fma_f32 v[8:9], v[70:71], v[16:17], v[8:9] op_sel_hi:[0,1,1]
	v_mov_b32_e32 v12, v14
	v_mov_b32_e32 v13, v18
	v_pk_fma_f32 v[8:9], v[72:73], v[12:13], v[8:9] op_sel_hi:[0,1,1]
	v_mov_b32_e32 v18, v15
	v_pk_fma_f32 v[8:9], v[76:77], v[18:19], v[8:9] op_sel_hi:[0,1,1]
	ds_read_b96 v[12:14], v49 offset:8224
	ds_read_b96 v[16:18], v49 offset:12320
	v_add_u32_e32 v19, 0x302c, v49
	s_waitcnt lgkmcnt(1)
	v_mov_b32_e32 v88, v12
	s_waitcnt lgkmcnt(0)
	v_mov_b32_e32 v89, v16
	v_pk_fma_f32 v[8:9], v[74:75], v[88:89], v[8:9] op_sel_hi:[0,1,1]
	ds_read_b128 v[88:91], v49 offset:16384
	ds_read_b128 v[92:95], v49 offset:20480
	v_mov_b32_e32 v16, v13
	v_pk_fma_f32 v[12:13], v[78:79], v[16:17], v[8:9] op_sel_hi:[0,1,1]
	v_mov_b32_e32 v11, v18
	s_waitcnt lgkmcnt(1)
	v_mov_b32_e32 v8, v88
	s_waitcnt lgkmcnt(0)
	v_mov_b32_e32 v9, v92
	v_pk_fma_f32 v[8:9], v[80:81], v[8:9], v[32:33] op_sel_hi:[0,1,1]
	v_mov_b32_e32 v92, v89
	v_pk_fma_f32 v[8:9], v[82:83], v[92:93], v[8:9] op_sel_hi:[0,1,1]
	v_mov_b32_e32 v16, v90
	v_mov_b32_e32 v17, v94
	v_pk_fma_f32 v[8:9], v[84:85], v[16:17], v[8:9] op_sel_hi:[0,1,1]
	v_mov_b32_e32 v94, v91
	v_pk_fma_f32 v[8:9], v[86:87], v[94:95], v[8:9] op_sel_hi:[0,1,1]
	ds_read_b128 v[88:91], v49 offset:16400
	ds_read_b128 v[92:95], v49 offset:20496
	v_add_u32_e32 v18, 0x202c, v49
	s_waitcnt lgkmcnt(1)
	v_mov_b32_e32 v16, v88
	s_waitcnt lgkmcnt(0)
	v_mov_b32_e32 v17, v92
	v_pk_fma_f32 v[8:9], v[68:69], v[16:17], v[8:9] op_sel_hi:[0,1,1]
	v_mov_b32_e32 v92, v89
	v_pk_fma_f32 v[8:9], v[70:71], v[92:93], v[8:9] op_sel_hi:[0,1,1]
	v_mov_b32_e32 v16, v90
	v_mov_b32_e32 v17, v94
	v_pk_fma_f32 v[8:9], v[72:73], v[16:17], v[8:9] op_sel_hi:[0,1,1]
	v_mov_b32_e32 v94, v91
	v_pk_fma_f32 v[8:9], v[76:77], v[94:95], v[8:9] op_sel_hi:[0,1,1]
	ds_read_b96 v[94:96], v49 offset:16416
	ds_read_b96 v[98:100], v49 offset:20512
	s_waitcnt lgkmcnt(1)
	v_mov_b32_e32 v16, v94
	s_waitcnt lgkmcnt(0)
	v_mov_b32_e32 v17, v98
	v_mov_b32_e32 v98, v95
	ds_read_b128 v[88:91], v49 offset:24576
	ds_read_b128 v[92:95], v49 offset:28672
	v_pk_fma_f32 v[8:9], v[74:75], v[16:17], v[8:9] op_sel_hi:[0,1,1]
	v_pk_fma_f32 v[16:17], v[78:79], v[98:99], v[8:9] op_sel_hi:[0,1,1]
	v_mov_b32_e32 v7, v100
	s_waitcnt lgkmcnt(1)
	v_mov_b32_e32 v8, v88
	s_waitcnt lgkmcnt(0)
	v_mov_b32_e32 v9, v92
	v_pk_fma_f32 v[8:9], v[80:81], v[8:9], v[44:45] op_sel_hi:[0,1,1]
	v_mov_b32_e32 v92, v89
	v_pk_fma_f32 v[8:9], v[82:83], v[92:93], v[8:9] op_sel_hi:[0,1,1]
	v_mov_b32_e32 v32, v90
	v_mov_b32_e32 v33, v94
	v_pk_fma_f32 v[8:9], v[84:85], v[32:33], v[8:9] op_sel_hi:[0,1,1]
	v_mov_b32_e32 v94, v91
	v_pk_fma_f32 v[8:9], v[86:87], v[94:95], v[8:9] op_sel_hi:[0,1,1]
	ds_read_b128 v[80:83], v49 offset:24592
	ds_read_b128 v[84:87], v49 offset:28688
	v_add_u32_e32 v44, 0x402c, v49
	v_add_u32_e32 v45, 0x502c, v49
	v_add_u32_e32 v88, 0x604c, v49
	s_waitcnt lgkmcnt(1)
	v_mov_b32_e32 v32, v80
	s_waitcnt lgkmcnt(0)
	v_mov_b32_e32 v33, v84
	v_pk_fma_f32 v[8:9], v[68:69], v[32:33], v[8:9] op_sel_hi:[0,1,1]
	v_mov_b32_e32 v84, v81
	v_pk_fma_f32 v[8:9], v[70:71], v[84:85], v[8:9] op_sel_hi:[0,1,1]
	v_mov_b32_e32 v32, v82
	ds_read_b96 v[68:70], v49 offset:24608
	ds_read_b96 v[80:82], v49 offset:28704
	v_mov_b32_e32 v33, v86
	v_pk_fma_f32 v[8:9], v[72:73], v[32:33], v[8:9] op_sel_hi:[0,1,1]
	v_mov_b32_e32 v86, v83
	s_waitcnt lgkmcnt(1)
	v_mov_b32_e32 v32, v68
	s_waitcnt lgkmcnt(0)
	v_mov_b32_e32 v33, v80
	v_mov_b32_e32 v80, v69
	v_mov_b32_e32 v0, v70
	ds_read_b128 v[68:71], v49 offset:32816
	v_pk_fma_f32 v[8:9], v[76:77], v[86:87], v[8:9] op_sel_hi:[0,1,1]
	v_pk_fma_f32 v[8:9], v[74:75], v[32:33], v[8:9] op_sel_hi:[0,1,1]
	v_pk_fma_f32 v[32:33], v[78:79], v[80:81], v[8:9] op_sel_hi:[0,1,1]
	v_mov_b32_e32 v8, v6
	s_waitcnt vmcnt(19) lgkmcnt(0)
	v_fmac_f32_e32 v29, v54, v68
	s_waitcnt vmcnt(18)
	v_fmac_f32_e32 v29, v52, v69
	v_mov_b32_e32 v9, v10
	s_waitcnt vmcnt(17)
	v_fmac_f32_e32 v29, v58, v70
	v_mov_b32_e32 v10, v14
	v_add_u32_e32 v14, 0x102c, v49
	s_waitcnt vmcnt(16)
	v_fmac_f32_e32 v29, v56, v71
	ds_read_b128 v[68:71], v49 offset:32832
	v_pk_fma_f32 v[2:3], v[50:51], v[8:9], v[4:5] op_sel_hi:[0,1,1]
	ds_read2_b32 v[4:5], v49 offset0:11 offset1:12
	ds_read2_b32 v[8:9], v14 offset1:1
	v_add_u32_e32 v72, 0x103c, v49
	v_add_u32_e32 v73, 0x203c, v49
	s_waitcnt vmcnt(15) lgkmcnt(2)
	v_fmac_f32_e32 v29, v62, v68
	s_waitcnt lgkmcnt(1)
	v_mov_b32_e32 v14, v4
	s_waitcnt lgkmcnt(0)
	v_mov_b32_e32 v15, v8
	v_pk_fma_f32 v[2:3], v[48:49], v[14:15], v[2:3] op_sel_hi:[0,1,1]
	v_mov_b32_e32 v8, v5
	v_pk_fma_f32 v[2:3], v[54:55], v[8:9], v[2:3] op_sel_hi:[0,1,1]
	ds_read2_b32 v[4:5], v49 offset0:13 offset1:14
	ds_read2_b32 v[8:9], v53 offset1:1
	v_add_u32_e32 v68, 0x1044, v49
	s_waitcnt vmcnt(14)
	v_fmac_f32_e32 v29, v60, v69
	v_add_u32_e32 v69, 0x104c, v49
	s_waitcnt lgkmcnt(1)
	v_mov_b32_e32 v14, v4
	s_waitcnt lgkmcnt(0)
	v_mov_b32_e32 v15, v8
	v_pk_fma_f32 v[2:3], v[52:53], v[14:15], v[2:3] op_sel_hi:[0,1,1]
	v_mov_b32_e32 v8, v5
	v_pk_fma_f32 v[2:3], v[58:59], v[8:9], v[2:3] op_sel_hi:[0,1,1]
	ds_read2_b32 v[4:5], v49 offset0:15 offset1:16
	ds_read2_b32 v[8:9], v72 offset1:1
	v_add_u32_e32 v74, 0x303c, v49
	v_add_u32_e32 v79, 0x2044, v49
	v_add_u32_e32 v80, 0x3044, v49
	s_waitcnt lgkmcnt(1)
	v_mov_b32_e32 v14, v4
	s_waitcnt lgkmcnt(0)
	v_mov_b32_e32 v15, v8
	v_pk_fma_f32 v[2:3], v[56:57], v[14:15], v[2:3] op_sel_hi:[0,1,1]
	v_mov_b32_e32 v8, v5
	v_pk_fma_f32 v[2:3], v[62:63], v[8:9], v[2:3] op_sel_hi:[0,1,1]
	ds_read2_b32 v[4:5], v49 offset0:17 offset1:18
	ds_read2_b32 v[8:9], v68 offset1:1
	s_waitcnt vmcnt(13)
	v_fmac_f32_e32 v29, v66, v70
	v_add_u32_e32 v70, 0x204c, v49
	v_add_u32_e32 v85, 0x304c, v49
	s_waitcnt lgkmcnt(1)
	v_mov_b32_e32 v14, v4
	s_waitcnt lgkmcnt(0)
	v_mov_b32_e32 v15, v8
	v_pk_fma_f32 v[2:3], v[60:61], v[14:15], v[2:3] op_sel_hi:[0,1,1]
	v_mov_b32_e32 v8, v5
	v_pk_fma_f32 v[2:3], v[66:67], v[8:9], v[2:3] op_sel_hi:[0,1,1]
	ds_read2_b32 v[4:5], v49 offset0:19 offset1:20
	ds_read2_b32 v[8:9], v69 offset1:1
	v_mov_b32_e32 v6, v96
	v_add_u32_e32 v75, 0x403c, v49
	v_add_u32_e32 v76, 0x503c, v49
	s_waitcnt lgkmcnt(1)
	v_mov_b32_e32 v14, v4
	s_waitcnt lgkmcnt(0)
	v_mov_b32_e32 v15, v8
	s_waitcnt vmcnt(12)
	v_pk_fma_f32 v[2:3], v[64:65], v[14:15], v[2:3] op_sel_hi:[0,1,1]
	v_mov_b32_e32 v8, v5
	s_waitcnt vmcnt(11)
	v_pk_fma_f32 v[8:9], v[46:47], v[8:9], v[2:3] op_sel_hi:[0,1,1]
	v_pk_fma_f32 v[2:3], v[50:51], v[10:11], v[12:13] op_sel_hi:[0,1,1]
	ds_read2_b32 v[4:5], v18 offset1:1
	ds_read2_b32 v[10:11], v19 offset1:1
	v_add_u32_e32 v81, 0x4044, v49
	v_mov_b32_e32 v1, v82
	v_add_u32_e32 v82, 0x5044, v49
	s_waitcnt lgkmcnt(1)
	v_mov_b32_e32 v12, v4
	s_waitcnt lgkmcnt(0)
	v_mov_b32_e32 v13, v10
	v_pk_fma_f32 v[2:3], v[48:49], v[12:13], v[2:3] op_sel_hi:[0,1,1]
	v_mov_b32_e32 v10, v5
	v_pk_fma_f32 v[2:3], v[54:55], v[10:11], v[2:3] op_sel_hi:[0,1,1]
	ds_read2_b32 v[4:5], v55 offset1:1
	ds_read2_b32 v[10:11], v57 offset1:1
	v_add_u32_e32 v86, 0x404c, v49
	v_add_u32_e32 v87, 0x504c, v49
	v_pk_fma_f32 v[0:1], v[50:51], v[0:1], v[32:33] op_sel_hi:[0,1,1]
	s_waitcnt lgkmcnt(1)
	v_mov_b32_e32 v12, v4
	s_waitcnt lgkmcnt(0)
	v_mov_b32_e32 v13, v10
	v_pk_fma_f32 v[2:3], v[52:53], v[12:13], v[2:3] op_sel_hi:[0,1,1]
	v_mov_b32_e32 v10, v5
	v_pk_fma_f32 v[2:3], v[58:59], v[10:11], v[2:3] op_sel_hi:[0,1,1]
	ds_read2_b32 v[4:5], v73 offset1:1
	ds_read2_b32 v[10:11], v74 offset1:1
	v_add_u32_e32 v77, 0x603c, v49
	v_add_u32_e32 v78, 0x703c, v49
	v_add_u32_e32 v83, 0x6044, v49
	s_waitcnt lgkmcnt(1)
	v_mov_b32_e32 v12, v4
	s_waitcnt lgkmcnt(0)
	v_mov_b32_e32 v13, v10
	v_pk_fma_f32 v[2:3], v[56:57], v[12:13], v[2:3] op_sel_hi:[0,1,1]
	v_mov_b32_e32 v10, v5
	v_pk_fma_f32 v[2:3], v[62:63], v[10:11], v[2:3] op_sel_hi:[0,1,1]
	ds_read2_b32 v[4:5], v79 offset1:1
	ds_read2_b32 v[10:11], v80 offset1:1
	v_add_u32_e32 v84, 0x7044, v49
	v_add_u32_e32 v89, 0x704c, v49
	v_fmac_f32_e32 v29, v64, v71
	s_waitcnt lgkmcnt(1)
	v_mov_b32_e32 v12, v4
	s_waitcnt lgkmcnt(0)
	v_mov_b32_e32 v13, v10
	v_pk_fma_f32 v[2:3], v[60:61], v[12:13], v[2:3] op_sel_hi:[0,1,1]
	v_mov_b32_e32 v10, v5
	v_pk_fma_f32 v[2:3], v[66:67], v[10:11], v[2:3] op_sel_hi:[0,1,1]
	ds_read2_b32 v[4:5], v70 offset1:1
	ds_read2_b32 v[10:11], v85 offset1:1
	v_add_u32_e32 v32, 0x1058, v49
	s_waitcnt lgkmcnt(1)
	v_mov_b32_e32 v12, v4
	s_waitcnt lgkmcnt(0)
	v_mov_b32_e32 v13, v10
	v_pk_fma_f32 v[2:3], v[64:65], v[12:13], v[2:3] op_sel_hi:[0,1,1]
	v_mov_b32_e32 v10, v5
	v_pk_fma_f32 v[12:13], v[46:47], v[10:11], v[2:3] op_sel_hi:[0,1,1]
	v_pk_fma_f32 v[2:3], v[50:51], v[6:7], v[16:17] op_sel_hi:[0,1,1]
	ds_read2_b32 v[4:5], v44 offset1:1
	ds_read2_b32 v[6:7], v45 offset1:1
	v_add_u32_e32 v44, 0x1068, v49
	v_add_u32_e32 v45, 0x7058, v49
	v_add_u32_e32 v50, 0x7068, v49
	s_waitcnt lgkmcnt(1)
	v_mov_b32_e32 v10, v4
	s_waitcnt lgkmcnt(0)
	v_mov_b32_e32 v11, v6
	v_pk_fma_f32 v[2:3], v[48:49], v[10:11], v[2:3] op_sel_hi:[0,1,1]
	v_mov_b32_e32 v6, v5
	v_pk_fma_f32 v[2:3], v[54:55], v[6:7], v[2:3] op_sel_hi:[0,1,1]
	ds_read2_b32 v[4:5], v59 offset1:1
	ds_read2_b32 v[6:7], v61 offset1:1
	s_waitcnt lgkmcnt(1)
	v_mov_b32_e32 v10, v4
	s_waitcnt lgkmcnt(0)
	v_mov_b32_e32 v11, v6
	v_pk_fma_f32 v[2:3], v[52:53], v[10:11], v[2:3] op_sel_hi:[0,1,1]
	v_mov_b32_e32 v6, v5
	v_pk_fma_f32 v[2:3], v[58:59], v[6:7], v[2:3] op_sel_hi:[0,1,1]
	ds_read2_b32 v[4:5], v75 offset1:1
	ds_read2_b32 v[6:7], v76 offset1:1
	s_waitcnt lgkmcnt(1)
	v_mov_b32_e32 v10, v4
	s_waitcnt lgkmcnt(0)
	v_mov_b32_e32 v11, v6
	v_pk_fma_f32 v[2:3], v[56:57], v[10:11], v[2:3] op_sel_hi:[0,1,1]
	v_mov_b32_e32 v6, v5
	v_pk_fma_f32 v[2:3], v[62:63], v[6:7], v[2:3] op_sel_hi:[0,1,1]
	ds_read2_b32 v[4:5], v81 offset1:1
	ds_read2_b32 v[6:7], v82 offset1:1
	s_waitcnt lgkmcnt(1)
	v_mov_b32_e32 v10, v4
	s_waitcnt lgkmcnt(0)
	v_mov_b32_e32 v11, v6
	v_pk_fma_f32 v[2:3], v[60:61], v[10:11], v[2:3] op_sel_hi:[0,1,1]
	v_mov_b32_e32 v6, v5
	v_pk_fma_f32 v[2:3], v[66:67], v[6:7], v[2:3] op_sel_hi:[0,1,1]
	ds_read2_b32 v[4:5], v86 offset1:1
	ds_read2_b32 v[6:7], v87 offset1:1
	s_waitcnt lgkmcnt(1)
	v_mov_b32_e32 v10, v4
	s_waitcnt lgkmcnt(0)
	v_mov_b32_e32 v11, v6
	v_pk_fma_f32 v[2:3], v[64:65], v[10:11], v[2:3] op_sel_hi:[0,1,1]
	v_mov_b32_e32 v6, v5
	v_pk_fma_f32 v[10:11], v[46:47], v[6:7], v[2:3] op_sel_hi:[0,1,1]
	ds_read2_b32 v[2:3], v47 offset1:1
	ds_read2_b32 v[4:5], v51 offset1:1
	v_add_u32_e32 v51, 0x2058, v49
	s_waitcnt lgkmcnt(1)
	v_mov_b32_e32 v6, v2
	s_waitcnt lgkmcnt(0)
	v_mov_b32_e32 v7, v4
	v_pk_fma_f32 v[0:1], v[48:49], v[6:7], v[0:1] op_sel_hi:[0,1,1]
	v_mov_b32_e32 v4, v3
	v_pk_fma_f32 v[0:1], v[54:55], v[4:5], v[0:1] op_sel_hi:[0,1,1]
	ds_read2_b32 v[2:3], v63 offset1:1
	ds_read2_b32 v[4:5], v67 offset1:1
	v_add_u32_e32 v48, 0x6068, v49
	s_waitcnt lgkmcnt(1)
	v_mov_b32_e32 v6, v2
	s_waitcnt lgkmcnt(0)
	v_mov_b32_e32 v7, v4
	v_pk_fma_f32 v[0:1], v[52:53], v[6:7], v[0:1] op_sel_hi:[0,1,1]
	v_mov_b32_e32 v4, v3
	v_pk_fma_f32 v[0:1], v[58:59], v[4:5], v[0:1] op_sel_hi:[0,1,1]
	ds_read2_b32 v[2:3], v77 offset1:1
	ds_read2_b32 v[4:5], v78 offset1:1
	s_waitcnt lgkmcnt(1)
	v_mov_b32_e32 v6, v2
	s_waitcnt lgkmcnt(0)
	v_mov_b32_e32 v7, v4
	v_pk_fma_f32 v[0:1], v[56:57], v[6:7], v[0:1] op_sel_hi:[0,1,1]
	v_mov_b32_e32 v4, v3
	v_pk_fma_f32 v[0:1], v[62:63], v[4:5], v[0:1] op_sel_hi:[0,1,1]
	ds_read2_b32 v[2:3], v83 offset1:1
	ds_read2_b32 v[4:5], v84 offset1:1
	v_add_u32_e32 v63, 0x2068, v49
	v_add_u32_e32 v62, 0x5058, v49
	s_waitcnt lgkmcnt(1)
	v_mov_b32_e32 v6, v2
	s_waitcnt lgkmcnt(0)
	v_mov_b32_e32 v7, v4
	v_pk_fma_f32 v[0:1], v[60:61], v[6:7], v[0:1] op_sel_hi:[0,1,1]
	v_mov_b32_e32 v4, v3
	v_pk_fma_f32 v[0:1], v[66:67], v[4:5], v[0:1] op_sel_hi:[0,1,1]
	ds_read2_b32 v[2:3], v88 offset1:1
	ds_read2_b32 v[4:5], v89 offset1:1
	v_add_u32_e32 v60, 0x3058, v49
	v_add_u32_e32 v61, 0x4058, v49
	v_add_u32_e32 v66, 0x4068, v49
	s_waitcnt lgkmcnt(1)
	v_mov_b32_e32 v6, v2
	s_waitcnt lgkmcnt(0)
	v_mov_b32_e32 v7, v4
	v_pk_fma_f32 v[0:1], v[64:65], v[6:7], v[0:1] op_sel_hi:[0,1,1]
	v_mov_b32_e32 v4, v3
	v_pk_fma_f32 v[4:5], v[46:47], v[4:5], v[0:1] op_sel_hi:[0,1,1]
	ds_read_b32 v18, v49 offset:84
	ds_read_b32 v19, v49 offset:4180
	ds_read_b32 v16, v49 offset:8276
	ds_read_b32 v17, v49 offset:12372
	ds_read_b32 v14, v49 offset:16468
	ds_read_b32 v15, v49 offset:20564
	ds_read_b32 v6, v49 offset:24660
	ds_read_b32 v7, v49 offset:28756
	ds_read_b128 v[0:3], v49 offset:32848
	s_waitcnt vmcnt(10)
	v_mov_b32_e32 v47, v36
	s_waitcnt lgkmcnt(5)
	v_pk_fma_f32 v[12:13], v[36:37], v[16:17], v[12:13] op_sel_hi:[0,1,1]
	v_add_u32_e32 v64, 0x3068, v49
	s_waitcnt lgkmcnt(3)
	v_pk_fma_f32 v[10:11], v[36:37], v[14:15], v[10:11] op_sel_hi:[0,1,1]
	s_waitcnt lgkmcnt(0)
	v_pk_mul_f32 v[0:1], v[46:47], v[0:1]
	s_waitcnt vmcnt(8)
	v_pk_mul_f32 v[2:3], v[34:35], v[2:3]
	v_add_f32_e32 v0, v29, v0
	v_add_f32_e32 v0, v0, v1
	v_add_f32_e32 v0, v0, v2
	v_add_f32_e32 v33, v0, v3
	ds_read_b128 v[0:3], v49 offset:32864
	s_waitcnt vmcnt(2)
	v_mov_b32_e32 v46, v43
	v_add_u32_e32 v29, 0x6058, v49
	v_add_u32_e32 v67, 0x5068, v49
	s_waitcnt lgkmcnt(0)
	v_pk_mul_f32 v[0:1], v[38:39], v[0:1]
	s_nop 0
	v_add_f32_e32 v0, v33, v0
	v_add_f32_e32 v33, v0, v1
	v_pk_mul_f32 v[0:1], v[40:41], v[2:3]
	s_nop 0
	v_add_f32_e32 v0, v33, v0
	v_add_f32_e32 v33, v0, v1
	ds_read_b128 v[0:3], v49 offset:32880
	ds_read2_b64 v[52:55], v49 offset0:11 offset1:12
	ds_read2_b64 v[56:59], v32 offset1:1
	s_waitcnt lgkmcnt(2)
	v_pk_mul_f32 v[0:1], v[42:43], v[0:1]
	s_nop 0
	v_add_f32_e32 v0, v33, v0
	v_add_f32_e32 v47, v0, v1
	v_pk_fma_f32 v[0:1], v[36:37], v[18:19], v[8:9] op_sel_hi:[0,1,1]
	s_waitcnt lgkmcnt(1)
	v_mov_b32_e32 v8, v52
	s_waitcnt lgkmcnt(0)
	v_mov_b32_e32 v9, v56
	v_pk_fma_f32 v[8:9], v[34:35], v[8:9], v[0:1] op_sel_hi:[0,1,1]
	v_mov_b32_e32 v0, v35
	v_mov_b32_e32 v56, v53
	v_pk_fma_f32 v[8:9], v[0:1], v[56:57], v[8:9] op_sel_hi:[0,1,1]
	v_mov_b32_e32 v18, v54
	v_mov_b32_e32 v19, v58
	v_pk_fma_f32 v[8:9], v[38:39], v[18:19], v[8:9] op_sel_hi:[0,1,1]
	v_mov_b32_e32 v18, v39
	v_mov_b32_e32 v58, v55
	v_pk_fma_f32 v[8:9], v[18:19], v[58:59], v[8:9] op_sel_hi:[0,1,1]
	ds_read2_b64 v[52:55], v49 offset0:13 offset1:14
	ds_read2_b64 v[56:59], v44 offset1:1
	v_mov_b32_e32 v44, v41
	s_waitcnt lgkmcnt(1)
	v_mov_b32_e32 v32, v52
	s_waitcnt lgkmcnt(0)
	v_mov_b32_e32 v33, v56
	v_pk_fma_f32 v[8:9], v[40:41], v[32:33], v[8:9] op_sel_hi:[0,1,1]
	v_mov_b32_e32 v56, v53
	v_pk_fma_f32 v[8:9], v[44:45], v[56:57], v[8:9] op_sel_hi:[0,1,1]
	v_mov_b32_e32 v32, v54
	v_mov_b32_e32 v33, v58
	v_pk_fma_f32 v[8:9], v[42:43], v[32:33], v[8:9] op_sel_hi:[0,1,1]
	ds_read_b64 v[32:33], v49 offset:120
	ds_read_b64 v[52:53], v49 offset:4216
	v_mov_b32_e32 v58, v55
	v_pk_fma_f32 v[8:9], v[46:47], v[58:59], v[8:9] op_sel_hi:[0,1,1]
	s_waitcnt lgkmcnt(1)
	v_mov_b32_e32 v54, v32
	s_waitcnt lgkmcnt(0)
	v_mov_b32_e32 v55, v52
	s_waitcnt vmcnt(1)
	v_pk_fma_f32 v[8:9], v[28:29], v[54:55], v[8:9] op_sel_hi:[0,1,1]
	v_mov_b32_e32 v52, v33
	s_waitcnt vmcnt(0)
	v_pk_fma_f32 v[8:9], v[30:31], v[52:53], v[8:9] op_sel_hi:[0,1,1]
	ds_read2_b64 v[52:55], v51 offset1:1
	ds_read2_b64 v[56:59], v60 offset1:1
	s_waitcnt lgkmcnt(1)
	v_mov_b32_e32 v16, v52
	s_waitcnt lgkmcnt(0)
	v_mov_b32_e32 v17, v56
	v_pk_fma_f32 v[12:13], v[34:35], v[16:17], v[12:13] op_sel_hi:[0,1,1]
	v_mov_b32_e32 v56, v53
	v_pk_fma_f32 v[12:13], v[0:1], v[56:57], v[12:13] op_sel_hi:[0,1,1]
	v_mov_b32_e32 v16, v54
	v_mov_b32_e32 v17, v58
	v_pk_fma_f32 v[12:13], v[38:39], v[16:17], v[12:13] op_sel_hi:[0,1,1]
	v_mov_b32_e32 v58, v55
	v_pk_fma_f32 v[12:13], v[18:19], v[58:59], v[12:13] op_sel_hi:[0,1,1]
	ds_read2_b64 v[52:55], v63 offset1:1
	ds_read2_b64 v[56:59], v64 offset1:1
	s_waitcnt lgkmcnt(1)
	v_mov_b32_e32 v16, v52
	s_waitcnt lgkmcnt(0)
	v_mov_b32_e32 v17, v56
	v_pk_fma_f32 v[12:13], v[40:41], v[16:17], v[12:13] op_sel_hi:[0,1,1]
	v_mov_b32_e32 v56, v53
	v_pk_fma_f32 v[12:13], v[44:45], v[56:57], v[12:13] op_sel_hi:[0,1,1]
	v_mov_b32_e32 v16, v54
	v_mov_b32_e32 v17, v58
	v_pk_fma_f32 v[12:13], v[42:43], v[16:17], v[12:13] op_sel_hi:[0,1,1]
	ds_read_b64 v[16:17], v49 offset:8312
	ds_read_b64 v[32:33], v49 offset:12408
	v_mov_b32_e32 v58, v55
	v_pk_fma_f32 v[12:13], v[46:47], v[58:59], v[12:13] op_sel_hi:[0,1,1]
	s_waitcnt lgkmcnt(1)
	v_mov_b32_e32 v52, v16
	s_waitcnt lgkmcnt(0)
	v_mov_b32_e32 v53, v32
	v_pk_fma_f32 v[12:13], v[28:29], v[52:53], v[12:13] op_sel_hi:[0,1,1]
	v_mov_b32_e32 v32, v17
	ds_read2_b64 v[14:17], v61 offset1:1
	ds_read2_b64 v[52:55], v62 offset1:1
	v_pk_fma_f32 v[12:13], v[30:31], v[32:33], v[12:13] op_sel_hi:[0,1,1]
	s_waitcnt lgkmcnt(1)
	v_mov_b32_e32 v32, v14
	s_waitcnt lgkmcnt(0)
	v_mov_b32_e32 v33, v52
	v_pk_fma_f32 v[10:11], v[34:35], v[32:33], v[10:11] op_sel_hi:[0,1,1]
	v_mov_b32_e32 v52, v15
	v_pk_fma_f32 v[10:11], v[0:1], v[52:53], v[10:11] op_sel_hi:[0,1,1]
	v_mov_b32_e32 v14, v16
	v_mov_b32_e32 v15, v54
	v_pk_fma_f32 v[10:11], v[38:39], v[14:15], v[10:11] op_sel_hi:[0,1,1]
	v_mov_b32_e32 v54, v17
	v_pk_fma_f32 v[10:11], v[18:19], v[54:55], v[10:11] op_sel_hi:[0,1,1]
	ds_read2_b64 v[14:17], v66 offset1:1
	ds_read2_b64 v[52:55], v67 offset1:1
	s_waitcnt lgkmcnt(1)
	v_mov_b32_e32 v32, v14
	s_waitcnt lgkmcnt(0)
	v_mov_b32_e32 v33, v52
	v_pk_fma_f32 v[10:11], v[40:41], v[32:33], v[10:11] op_sel_hi:[0,1,1]
	v_mov_b32_e32 v52, v15
	v_pk_fma_f32 v[10:11], v[44:45], v[52:53], v[10:11] op_sel_hi:[0,1,1]
	v_mov_b32_e32 v14, v16
	v_mov_b32_e32 v15, v54
	v_pk_fma_f32 v[10:11], v[42:43], v[14:15], v[10:11] op_sel_hi:[0,1,1]
	v_mov_b32_e32 v54, v17
	ds_read_b64 v[14:15], v49 offset:16504
	ds_read_b64 v[16:17], v49 offset:20600
	v_pk_fma_f32 v[10:11], v[46:47], v[54:55], v[10:11] op_sel_hi:[0,1,1]
	s_waitcnt lgkmcnt(1)
	v_mov_b32_e32 v32, v14
	s_waitcnt lgkmcnt(0)
	v_mov_b32_e32 v33, v16
	v_pk_fma_f32 v[10:11], v[28:29], v[32:33], v[10:11] op_sel_hi:[0,1,1]
	v_mov_b32_e32 v16, v15
	v_pk_fma_f32 v[32:33], v[30:31], v[16:17], v[10:11] op_sel_hi:[0,1,1]
	v_pk_fma_f32 v[10:11], v[36:37], v[6:7], v[4:5] op_sel_hi:[0,1,1]
	ds_read2_b64 v[4:7], v29 offset1:1
	ds_read2_b64 v[14:17], v45 offset1:1
	s_waitcnt lgkmcnt(1)
	v_mov_b32_e32 v52, v4
	s_waitcnt lgkmcnt(0)
	v_mov_b32_e32 v53, v14
	v_pk_fma_f32 v[10:11], v[34:35], v[52:53], v[10:11] op_sel_hi:[0,1,1]
	v_mov_b32_e32 v14, v5
	v_pk_fma_f32 v[0:1], v[0:1], v[14:15], v[10:11] op_sel_hi:[0,1,1]
	v_mov_b32_e32 v4, v6
	v_mov_b32_e32 v5, v16
	v_pk_fma_f32 v[0:1], v[38:39], v[4:5], v[0:1] op_sel_hi:[0,1,1]
	v_mov_b32_e32 v16, v7
	v_pk_fma_f32 v[0:1], v[18:19], v[16:17], v[0:1] op_sel_hi:[0,1,1]
	ds_read2_b64 v[4:7], v48 offset1:1
	ds_read2_b64 v[14:17], v50 offset1:1
	s_waitcnt lgkmcnt(1)
	v_mov_b32_e32 v10, v4
	s_waitcnt lgkmcnt(0)
	v_mov_b32_e32 v11, v14
	v_pk_fma_f32 v[0:1], v[40:41], v[10:11], v[0:1] op_sel_hi:[0,1,1]
	v_mov_b32_e32 v14, v5
	v_pk_fma_f32 v[0:1], v[44:45], v[14:15], v[0:1] op_sel_hi:[0,1,1]
	v_mov_b32_e32 v4, v6
	v_mov_b32_e32 v5, v16
	v_pk_fma_f32 v[0:1], v[42:43], v[4:5], v[0:1] op_sel_hi:[0,1,1]
	v_mov_b32_e32 v16, v7
	ds_read_b64 v[4:5], v49 offset:24696
	ds_read_b64 v[6:7], v49 offset:28792
	v_pk_fma_f32 v[0:1], v[46:47], v[16:17], v[0:1] op_sel_hi:[0,1,1]
	v_add_u32_e32 v49, 0x80, v49
	s_waitcnt lgkmcnt(1)
	v_mov_b32_e32 v10, v4
	s_waitcnt lgkmcnt(0)
	v_mov_b32_e32 v11, v6
	v_pk_fma_f32 v[0:1], v[28:29], v[10:11], v[0:1] op_sel_hi:[0,1,1]
	v_mov_b32_e32 v6, v5
	v_mov_b32_e32 v29, v30
	v_pk_fma_f32 v[44:45], v[30:31], v[6:7], v[0:1] op_sel_hi:[0,1,1]
	v_pk_mul_f32 v[0:1], v[28:29], v[2:3]
	s_nop 0
	v_add_f32_e32 v0, v47, v0
	v_add_f32_e32 v29, v0, v1
	s_cbranch_scc0 .LBB0_2070
	v_lshl_add_u32 v0, v31, 2, 0
	s_movk_i32 s0, 0x900
	v_mad_u64_u32 v[2:3], s[0:1], v37, s0, v[0:1]
	s_movk_i32 s0, 0x240
	s_nop 0
	v_cmp_gt_i32_e32 vcc, s0, v20
	ds_write2st64_b32 v2, v8, v9 offset0:144 offset1:145
	ds_write2st64_b32 v2, v12, v13 offset0:146 offset1:147
	ds_write2st64_b32 v2, v32, v33 offset0:148 offset1:149
	ds_write2st64_b32 v2, v44, v45 offset0:150 offset1:151
	ds_write_b32 v2, v29 offset:38912
	s_waitcnt lgkmcnt(0)
	s_barrier
	s_and_saveexec_b64 s[34:35], vcc
	s_cbranch_execz .LBB0_1910
	s_add_i32 s0, s66, 0xfffffa00
	s_cmpk_lt_u32 s0, 0x180
	v_and_b32_e32 v2, 31, v20
	s_cselect_b64 vcc, -1, 0
	s_and_b32 s0, s45, 0x3fffff8
	v_lshlrev_b32_e32 v4, 1, v2
	s_cmp_eq_u32 s0, 32
	v_mov_b32_e32 v3, s66
	s_movk_i32 s0, 0x9e0
	v_subrev_u32_e32 v5, 31, v4
	v_cmp_gt_u32_e64 s[6:7], 16, v2
	v_bitop3_b32 v3, v31, s0, v3 bitop3:0xc8
	v_or_b32_e32 v1, s66, v31
	v_cndmask_b32_e64 v2, v5, v4, s[6:7]
	v_add_u32_e32 v2, v2, v3
	s_cselect_b64 s[6:7], -1, 0
	v_cndmask_b32_e64 v1, v1, v2, s[6:7]
	v_lshlrev_b32_e32 v2, 1, v31
	v_subrev_u32_e32 v3, 63, v2
	v_cmp_gt_u32_e64 s[6:7], 32, v31
	s_and_b32 s0, s66, 0x7c0
	s_mov_b64 s[56:57], -1
	v_cndmask_b32_e64 v2, v3, v2, s[6:7]
	v_add_u32_e32 v2, s0, v2
	v_cndmask_b32_e32 v2, v1, v2, vcc
	v_max_i32_e32 v1, 64, v20
	v_sub_u32_e32 v1, v1, v20
	v_ashrrev_i32_e32 v3, 31, v2
	v_add_u32_e32 v1, 0x1ff, v1
	s_movk_i32 s0, 0x1ff
	v_lshl_add_u64 v[2:3], v[2:3], 2, s[8:9]
	v_cmp_lt_u32_e32 vcc, s0, v1
	s_and_saveexec_b64 s[6:7], vcc
	s_cbranch_execz .LBB0_2076
	v_lshrrev_b32_e32 v1, 9, v1
	v_add_u32_e32 v1, 1, v1
	v_and_b32_e32 v6, 0xfffffe, v1
	s_mov_b64 s[56:57], 0
	v_mov_b32_e32 v7, v6
	v_mov_b64_e32 v[4:5], v[20:21]

.LBB0_2246:
	s_movk_i32 s4, 0x57f
	v_cmp_lt_i32_e32 vcc, s4, v0
	s_and_saveexec_b64 s[4:5], vcc
	s_xor_b64 s[4:5], exec, s[4:5]
	s_cbranch_execz .LBB0_2256
	s_movk_i32 s6, 0x77f
	v_cmp_lt_u32_e32 vcc, s6, v0
	v_add_u32_e32 v14, 0x600, v12
	s_and_saveexec_b64 s[6:7], vcc
	s_xor_b64 s[6:7], exec, s[6:7]
	s_cbranch_execz .LBB0_2253
	s_movk_i32 s16, 0xf7f
	v_cmp_lt_u32_e32 vcc, s16, v0
	s_and_saveexec_b64 s[16:17], vcc
	s_xor_b64 s[16:17], exec, s[16:17]
	s_cbranch_execz .LBB0_2250
	v_and_b32_e32 v17, 0x1ffc0, v38
	v_and_b32_e32 v16, 0x3e0, v14
	v_or_b32_e32 v14, v17, v1
	v_lshlrev_b32_e32 v14, 10, v14
	v_or3_b32 v14, v14, v13, v16
	v_lshlrev_b32_e32 v64, 2, v14
	v_lshl_add_u64 v[14:15], s[8:9], 0, v[64:65]
	v_add_co_u32_e32 v18, vcc, 0x2000, v14
	s_mov_b32 s18, 0x10000
	s_nop 0
	v_addc_co_u32_e32 v19, vcc, 0, v15, vcc
	global_load_dword v21, v[18:19], off nt
	v_add_co_u32_e32 v18, vcc, 0x4000, v14
	global_load_dword v20, v64, s[8:9]
	s_nop 0
	v_addc_co_u32_e32 v19, vcc, 0, v15, vcc
	global_load_dword v22, v[18:19], off nt
	v_add_co_u32_e32 v18, vcc, 0x6000, v14
	s_nop 1
	v_addc_co_u32_e32 v19, vcc, 0, v15, vcc
	global_load_dword v23, v[18:19], off nt
	v_add_co_u32_e32 v18, vcc, 0x8000, v14
	s_nop 1
	v_addc_co_u32_e32 v19, vcc, 0, v15, vcc
	global_load_dword v24, v[18:19], off nt
	v_add_co_u32_e32 v18, vcc, 0xa000, v14
	s_nop 1
	v_addc_co_u32_e32 v19, vcc, 0, v15, vcc
	global_load_dword v25, v[18:19], off nt
	v_add_co_u32_e32 v18, vcc, 0xc000, v14
	s_nop 1
	v_addc_co_u32_e32 v19, vcc, 0, v15, vcc
	global_load_dword v26, v[18:19], off nt
	v_add_co_u32_e32 v18, vcc, 0xe000, v14
	s_nop 1
	v_addc_co_u32_e32 v19, vcc, 0, v15, vcc
	global_load_dword v27, v[18:19], off nt
	v_add_co_u32_e32 v18, vcc, s18, v14
	s_mov_b32 s18, 0x12000
	s_nop 0
	v_addc_co_u32_e32 v19, vcc, 0, v15, vcc
	global_load_dword v39, v[18:19], off nt
	v_add_co_u32_e32 v18, vcc, s18, v14
	s_mov_b32 s18, 0x14000
	s_nop 0
	v_addc_co_u32_e32 v19, vcc, 0, v15, vcc
	global_load_dword v40, v[18:19], off nt
	v_add_co_u32_e32 v18, vcc, s18, v14
	s_mov_b32 s18, 0x16000
	s_nop 0
	v_addc_co_u32_e32 v19, vcc, 0, v15, vcc
	global_load_dword v41, v[18:19], off nt
	v_add_co_u32_e32 v18, vcc, s18, v14
	s_mov_b32 s18, 0x18000
	s_nop 0
	v_addc_co_u32_e32 v19, vcc, 0, v15, vcc
	global_load_dword v42, v[18:19], off nt
	v_add_co_u32_e32 v18, vcc, s18, v14
	s_mov_b32 s18, 0x1a000
	s_nop 0
	v_addc_co_u32_e32 v19, vcc, 0, v15, vcc
	global_load_dword v43, v[18:19], off nt
	v_add_co_u32_e32 v18, vcc, s18, v14
	s_mov_b32 s18, 0x1c000
	s_nop 0
	v_addc_co_u32_e32 v19, vcc, 0, v15, vcc
	global_load_dword v44, v[18:19], off nt
	v_add_co_u32_e32 v18, vcc, s18, v14
	s_mov_b32 s18, 0x1e000
	s_nop 0
	v_addc_co_u32_e32 v19, vcc, 0, v15, vcc
	global_load_dword v45, v[18:19], off nt
	v_add_co_u32_e32 v18, vcc, s18, v14
	s_mov_b32 s18, 0x20000
	s_nop 0
	v_addc_co_u32_e32 v19, vcc, 0, v15, vcc
	global_load_dword v46, v[18:19], off nt
	v_add_co_u32_e32 v18, vcc, s18, v14
	s_mov_b32 s18, 0x22000
	s_nop 0
	v_addc_co_u32_e32 v19, vcc, 0, v15, vcc
	global_load_dword v47, v[18:19], off nt
	v_add_co_u32_e32 v18, vcc, s18, v14
	s_mov_b32 s18, 0x24000
	s_nop 0
	v_addc_co_u32_e32 v19, vcc, 0, v15, vcc
	global_load_dword v48, v[18:19], off nt
	v_add_co_u32_e32 v18, vcc, s18, v14
	s_mov_b32 s18, 0x26000
	s_nop 0
	v_addc_co_u32_e32 v19, vcc, 0, v15, vcc
	global_load_dword v49, v[18:19], off nt
	v_add_co_u32_e32 v18, vcc, s18, v14
	s_mov_b32 s18, 0x28000
	s_nop 0
	v_addc_co_u32_e32 v19, vcc, 0, v15, vcc
	global_load_dword v50, v[18:19], off nt
	v_add_co_u32_e32 v18, vcc, s18, v14
	s_mov_b32 s18, 0x2a000
	s_nop 0
	v_addc_co_u32_e32 v19, vcc, 0, v15, vcc
	global_load_dword v51, v[18:19], off nt
	v_add_co_u32_e32 v18, vcc, s18, v14
	s_mov_b32 s18, 0x2c000
	s_nop 0
	v_addc_co_u32_e32 v19, vcc, 0, v15, vcc
	global_load_dword v52, v[18:19], off nt
	v_add_co_u32_e32 v18, vcc, s18, v14
	s_mov_b32 s18, 0x2e000
	s_nop 0
	v_addc_co_u32_e32 v19, vcc, 0, v15, vcc
	global_load_dword v53, v[18:19], off nt
	v_add_co_u32_e32 v18, vcc, s18, v14
	s_mov_b32 s18, 0x30000
	s_nop 0
	v_addc_co_u32_e32 v19, vcc, 0, v15, vcc
	global_load_dword v54, v[18:19], off nt
	v_add_co_u32_e32 v18, vcc, s18, v14
	s_mov_b32 s18, 0x32000
	s_nop 0
	v_addc_co_u32_e32 v19, vcc, 0, v15, vcc
	global_load_dword v55, v[18:19], off nt
	v_add_co_u32_e32 v18, vcc, s18, v14
	s_mov_b32 s18, 0x34000
	s_nop 0
	v_addc_co_u32_e32 v19, vcc, 0, v15, vcc
	global_load_dword v56, v[18:19], off nt
	v_add_co_u32_e32 v18, vcc, s18, v14
	s_mov_b32 s18, 0x36000
	s_nop 0
	v_addc_co_u32_e32 v19, vcc, 0, v15, vcc
	global_load_dword v57, v[18:19], off nt
	v_add_co_u32_e32 v18, vcc, s18, v14
	s_mov_b32 s18, 0x38000
	s_nop 0
	v_addc_co_u32_e32 v19, vcc, 0, v15, vcc
	global_load_dword v58, v[18:19], off nt
	v_add_co_u32_e32 v18, vcc, s18, v14
	s_mov_b32 s18, 0x3a000
	s_nop 0
	v_addc_co_u32_e32 v19, vcc, 0, v15, vcc
	global_load_dword v59, v[18:19], off nt
	v_add_co_u32_e32 v18, vcc, s18, v14
	s_mov_b32 s18, 0x3c000
	s_nop 0
	v_addc_co_u32_e32 v19, vcc, 0, v15, vcc
	global_load_dword v60, v[18:19], off nt
	v_add_co_u32_e32 v18, vcc, s18, v14
	s_mov_b32 s18, 0x3e000
	s_nop 0
	v_addc_co_u32_e32 v19, vcc, 0, v15, vcc
	v_add_co_u32_e32 v14, vcc, s18, v14
	global_load_dword v18, v[18:19], off nt
	s_nop 0
	v_addc_co_u32_e32 v15, vcc, 0, v15, vcc
	global_load_dword v14, v[14:15], off nt
	v_add_u32_e32 v15, 0x400, v28
	s_waitcnt vmcnt(0)
	ds_write2_b32 v28, v20, v21 offset1:66
	ds_write2_b32 v28, v22, v23 offset0:132 offset1:198
	ds_write2_b32 v15, v24, v25 offset0:8 offset1:74
	ds_write2_b32 v15, v26, v27 offset0:140 offset1:206
	v_add_u32_e32 v15, 0x800, v28
	ds_write2_b32 v15, v39, v40 offset0:16 offset1:82
	ds_write2_b32 v15, v41, v42 offset0:148 offset1:214
	v_add_u32_e32 v15, 0xc00, v28
	ds_write2_b32 v15, v43, v44 offset0:24 offset1:90
	ds_write2_b32 v15, v45, v46 offset0:156 offset1:222
	v_add_u32_e32 v15, 0x1000, v28
	ds_write2_b32 v15, v47, v48 offset0:32 offset1:98
	ds_write2_b32 v15, v49, v50 offset0:164 offset1:230
	v_add_u32_e32 v15, 0x1400, v28
	ds_write2_b32 v15, v51, v52 offset0:40 offset1:106
	ds_write2_b32 v15, v53, v54 offset0:172 offset1:238
	v_add_u32_e32 v15, 0x1800, v28
	ds_write2_b32 v15, v55, v56 offset0:48 offset1:114
	ds_write2_b32 v15, v57, v58 offset0:180 offset1:246
	v_add_u32_e32 v15, 0x1c00, v28
	ds_write2_b32 v15, v59, v60 offset0:56 offset1:122
	ds_write2_b32 v15, v18, v14 offset0:188 offset1:254
	s_waitcnt lgkmcnt(0)
	ds_read2_b32 v[22:23], v30 offset0:33 offset1:41
	ds_read2_b32 v[24:25], v30 offset1:8
	ds_read2_b32 v[26:27], v30 offset0:66 offset1:74
	ds_read2_b32 v[40:41], v30 offset0:99 offset1:107
	ds_read2_b32 v[42:43], v30 offset0:132 offset1:140
	ds_read2_b32 v[44:45], v30 offset0:165 offset1:173
	ds_read2_b32 v[46:47], v30 offset0:198 offset1:206
	ds_read2_b32 v[48:49], v30 offset0:231 offset1:239
	v_lshlrev_b32_e32 v64, 1, v17
	v_or_b32_e32 v17, v16, v29
	v_lshl_add_u64 v[14:15], v[2:3], 0, v[64:65]
	v_lshlrev_b32_e32 v64, 13, v17
	v_or_b32_e32 v17, v16, v31
	s_waitcnt lgkmcnt(0)
	v_cvt_pk_bf16_f32 v18, v24, v22
	v_cvt_pk_bf16_f32 v19, v26, v40
	v_cvt_pk_bf16_f32 v20, v42, v44
	v_cvt_pk_bf16_f32 v21, v46, v48
	v_lshl_add_u64 v[50:51], v[14:15], 0, v[64:65]
	v_lshlrev_b32_e32 v64, 13, v17
	global_store_dwordx4 v[50:51], v[18:21], off sc1
	v_or_b32_e32 v17, v16, v32
	v_or_b32_e32 v16, v16, v33
	v_cvt_pk_bf16_f32 v18, v25, v23
	v_cvt_pk_bf16_f32 v19, v27, v41
	v_cvt_pk_bf16_f32 v20, v43, v45
	v_cvt_pk_bf16_f32 v21, v47, v49
	v_lshl_add_u64 v[22:23], v[14:15], 0, v[64:65]
	global_store_dwordx4 v[22:23], v[18:21], off sc1
	ds_read2_b32 v[22:23], v30 offset0:49 offset1:57
	ds_read2_b32 v[24:25], v30 offset0:16 offset1:24
	ds_read2_b32 v[26:27], v30 offset0:82 offset1:90
	ds_read2_b32 v[40:41], v30 offset0:115 offset1:123
	ds_read2_b32 v[42:43], v30 offset0:148 offset1:156
	ds_read2_b32 v[44:45], v30 offset0:181 offset1:189
	ds_read2_b32 v[46:47], v30 offset0:214 offset1:222
	ds_read2_b32 v[48:49], v30 offset0:247 offset1:255
	v_lshlrev_b32_e32 v64, 13, v17
	s_waitcnt lgkmcnt(6)
	v_cvt_pk_bf16_f32 v18, v24, v22
	s_waitcnt lgkmcnt(4)
	v_cvt_pk_bf16_f32 v19, v26, v40
	s_waitcnt lgkmcnt(2)
	v_cvt_pk_bf16_f32 v20, v42, v44
	s_waitcnt lgkmcnt(0)
	v_cvt_pk_bf16_f32 v21, v46, v48
	v_lshl_add_u64 v[50:51], v[14:15], 0, v[64:65]
	v_lshlrev_b32_e32 v64, 13, v16
	global_store_dwordx4 v[50:51], v[18:21], off sc1
	v_lshl_add_u64 v[14:15], v[14:15], 0, v[64:65]
	s_nop 0
	v_cvt_pk_bf16_f32 v18, v25, v23
	v_cvt_pk_bf16_f32 v19, v27, v41
	v_cvt_pk_bf16_f32 v20, v43, v45
	v_cvt_pk_bf16_f32 v21, v47, v49
	global_store_dwordx4 v[14:15], v[18:21], off sc1
	s_waitcnt lgkmcnt(0)
.LBB0_2250:
	s_andn2_saveexec_b64 s[16:17], s[16:17]
	s_cbranch_execz .LBB0_2252
	v_add_u32_e32 v15, 0xf880, v0
	v_lshrrev_b32_e32 v15, 1, v15
	v_and_b32_e32 v17, 0x7fc0, v15
	v_and_b32_e32 v16, 0xfe0, v14
	v_or_b32_e32 v14, v17, v1
	v_lshlrev_b32_e32 v14, 12, v14
	v_or3_b32 v14, v14, v13, v16
	v_lshlrev_b32_e32 v64, 2, v14
	v_lshl_add_u64 v[14:15], s[10:11], 0, v[64:65]
	v_add_co_u32_e32 v18, vcc, 0x8000, v14
	s_mov_b32 s18, 0x10000
	s_nop 0
	v_addc_co_u32_e32 v19, vcc, 0, v15, vcc
	global_load_dword v21, v[18:19], off nt
	v_add_co_u32_e32 v18, vcc, s18, v14
	s_mov_b32 s18, 0x18000
	s_nop 0
	v_addc_co_u32_e32 v19, vcc, 0, v15, vcc
	global_load_dword v22, v[18:19], off nt
	v_add_co_u32_e32 v18, vcc, s18, v14
	global_load_dword v20, v64, s[10:11]
	s_nop 0
	v_addc_co_u32_e32 v19, vcc, 0, v15, vcc
	global_load_dword v23, v[18:19], off nt
	v_add_co_u32_e32 v18, vcc, 0x20000, v14
	s_nop 1
	v_addc_co_u32_e32 v19, vcc, 0, v15, vcc
	global_load_dword v24, v[18:19], off nt
	v_add_co_u32_e32 v18, vcc, 0x28000, v14
	s_nop 1
	v_addc_co_u32_e32 v19, vcc, 0, v15, vcc
	global_load_dword v25, v[18:19], off nt
	v_add_co_u32_e32 v18, vcc, 0x30000, v14
	s_nop 1
	v_addc_co_u32_e32 v19, vcc, 0, v15, vcc
	global_load_dword v26, v[18:19], off nt
	v_add_co_u32_e32 v18, vcc, 0x38000, v14
	s_nop 1
	v_addc_co_u32_e32 v19, vcc, 0, v15, vcc
	global_load_dword v27, v[18:19], off nt
	v_add_co_u32_e32 v18, vcc, 0x40000, v14
	s_nop 1
	v_addc_co_u32_e32 v19, vcc, 0, v15, vcc
	global_load_dword v39, v[18:19], off nt
	v_add_co_u32_e32 v18, vcc, 0x48000, v14
	s_nop 1
	v_addc_co_u32_e32 v19, vcc, 0, v15, vcc
	global_load_dword v40, v[18:19], off nt
	v_add_co_u32_e32 v18, vcc, 0x50000, v14
	s_nop 1
	v_addc_co_u32_e32 v19, vcc, 0, v15, vcc
	global_load_dword v41, v[18:19], off nt
	v_add_co_u32_e32 v18, vcc, 0x58000, v14
	s_nop 1
	v_addc_co_u32_e32 v19, vcc, 0, v15, vcc
	global_load_dword v42, v[18:19], off nt
	v_add_co_u32_e32 v18, vcc, 0x60000, v14
	s_nop 1
	v_addc_co_u32_e32 v19, vcc, 0, v15, vcc
	global_load_dword v43, v[18:19], off nt
	v_add_co_u32_e32 v18, vcc, 0x68000, v14
	s_nop 1
	v_addc_co_u32_e32 v19, vcc, 0, v15, vcc
	global_load_dword v44, v[18:19], off nt
	v_add_co_u32_e32 v18, vcc, 0x70000, v14
	s_nop 1
	v_addc_co_u32_e32 v19, vcc, 0, v15, vcc
	global_load_dword v45, v[18:19], off nt
	v_add_co_u32_e32 v18, vcc, 0x78000, v14
	s_nop 1
	v_addc_co_u32_e32 v19, vcc, 0, v15, vcc
	global_load_dword v46, v[18:19], off nt
	v_add_co_u32_e32 v18, vcc, 0x80000, v14
	s_nop 1
	v_addc_co_u32_e32 v19, vcc, 0, v15, vcc
	global_load_dword v47, v[18:19], off nt
	v_add_co_u32_e32 v18, vcc, 0x88000, v14
	s_nop 1
	v_addc_co_u32_e32 v19, vcc, 0, v15, vcc
	global_load_dword v48, v[18:19], off nt
	v_add_co_u32_e32 v18, vcc, 0x90000, v14
	s_nop 1
	v_addc_co_u32_e32 v19, vcc, 0, v15, vcc
	global_load_dword v49, v[18:19], off nt
	v_add_co_u32_e32 v18, vcc, 0x98000, v14
	s_nop 1
	v_addc_co_u32_e32 v19, vcc, 0, v15, vcc
	global_load_dword v50, v[18:19], off nt
	v_add_co_u32_e32 v18, vcc, 0xa0000, v14
	s_nop 1
	v_addc_co_u32_e32 v19, vcc, 0, v15, vcc
	global_load_dword v51, v[18:19], off nt
	v_add_co_u32_e32 v18, vcc, 0xa8000, v14
	s_nop 1
	v_addc_co_u32_e32 v19, vcc, 0, v15, vcc
	global_load_dword v52, v[18:19], off nt
	v_add_co_u32_e32 v18, vcc, 0xb0000, v14
	s_nop 1
	v_addc_co_u32_e32 v19, vcc, 0, v15, vcc
	global_load_dword v53, v[18:19], off nt
	v_add_co_u32_e32 v18, vcc, 0xb8000, v14
	s_nop 1
	v_addc_co_u32_e32 v19, vcc, 0, v15, vcc
	global_load_dword v54, v[18:19], off nt
	v_add_co_u32_e32 v18, vcc, 0xc0000, v14
	s_nop 1
	v_addc_co_u32_e32 v19, vcc, 0, v15, vcc
	global_load_dword v55, v[18:19], off nt
	v_add_co_u32_e32 v18, vcc, 0xc8000, v14
	s_nop 1
	v_addc_co_u32_e32 v19, vcc, 0, v15, vcc
	global_load_dword v56, v[18:19], off nt
	v_add_co_u32_e32 v18, vcc, 0xd0000, v14
	s_nop 1
	v_addc_co_u32_e32 v19, vcc, 0, v15, vcc
	global_load_dword v57, v[18:19], off nt
	v_add_co_u32_e32 v18, vcc, 0xd8000, v14
	s_nop 1
	v_addc_co_u32_e32 v19, vcc, 0, v15, vcc
	global_load_dword v58, v[18:19], off nt
	v_add_co_u32_e32 v18, vcc, 0xe0000, v14
	s_nop 1
	v_addc_co_u32_e32 v19, vcc, 0, v15, vcc
	global_load_dword v59, v[18:19], off nt
	v_add_co_u32_e32 v18, vcc, 0xe8000, v14
	s_nop 1
	v_addc_co_u32_e32 v19, vcc, 0, v15, vcc
	global_load_dword v60, v[18:19], off nt
	v_add_co_u32_e32 v18, vcc, 0xf0000, v14
	s_nop 1
	v_addc_co_u32_e32 v19, vcc, 0, v15, vcc
	v_add_co_u32_e32 v14, vcc, 0xf8000, v14
	global_load_dword v18, v[18:19], off nt
	s_nop 0
	v_addc_co_u32_e32 v15, vcc, 0, v15, vcc
	global_load_dword v14, v[14:15], off nt
	v_add_u32_e32 v15, 0x400, v28
	s_waitcnt vmcnt(0)
	ds_write2_b32 v28, v20, v21 offset1:66
	ds_write2_b32 v28, v22, v23 offset0:132 offset1:198
	ds_write2_b32 v15, v24, v25 offset0:8 offset1:74
	ds_write2_b32 v15, v26, v27 offset0:140 offset1:206
	v_add_u32_e32 v15, 0x800, v28
	ds_write2_b32 v15, v39, v40 offset0:16 offset1:82
	ds_write2_b32 v15, v41, v42 offset0:148 offset1:214
	v_add_u32_e32 v15, 0xc00, v28
	ds_write2_b32 v15, v43, v44 offset0:24 offset1:90
	ds_write2_b32 v15, v45, v46 offset0:156 offset1:222
	v_add_u32_e32 v15, 0x1000, v28
	ds_write2_b32 v15, v47, v48 offset0:32 offset1:98
	ds_write2_b32 v15, v49, v50 offset0:164 offset1:230
	v_add_u32_e32 v15, 0x1400, v28
	ds_write2_b32 v15, v51, v52 offset0:40 offset1:106
	ds_write2_b32 v15, v53, v54 offset0:172 offset1:238
	v_add_u32_e32 v15, 0x1800, v28
	ds_write2_b32 v15, v55, v56 offset0:48 offset1:114
	ds_write2_b32 v15, v57, v58 offset0:180 offset1:246
	v_add_u32_e32 v15, 0x1c00, v28
	ds_write2_b32 v15, v59, v60 offset0:56 offset1:122
	ds_write2_b32 v15, v18, v14 offset0:188 offset1:254
	s_waitcnt lgkmcnt(0)
	ds_read2_b32 v[22:23], v30 offset0:33 offset1:41
	ds_read2_b32 v[24:25], v30 offset1:8
	ds_read2_b32 v[26:27], v30 offset0:66 offset1:74
	ds_read2_b32 v[40:41], v30 offset0:99 offset1:107
	ds_read2_b32 v[42:43], v30 offset0:132 offset1:140
	ds_read2_b32 v[44:45], v30 offset0:165 offset1:173
	ds_read2_b32 v[46:47], v30 offset0:198 offset1:206
	ds_read2_b32 v[48:49], v30 offset0:231 offset1:239
	v_lshlrev_b32_e32 v64, 1, v17
	v_or_b32_e32 v17, v16, v29
	v_lshl_add_u64 v[14:15], v[4:5], 0, v[64:65]
	v_lshlrev_b32_e32 v64, 11, v17
	v_or_b32_e32 v17, v16, v31
	s_waitcnt lgkmcnt(0)
	v_cvt_pk_bf16_f32 v18, v24, v22
	v_cvt_pk_bf16_f32 v19, v26, v40
	v_cvt_pk_bf16_f32 v20, v42, v44
	v_cvt_pk_bf16_f32 v21, v46, v48
	v_lshl_add_u64 v[50:51], v[14:15], 0, v[64:65]
	v_lshlrev_b32_e32 v64, 11, v17
	global_store_dwordx4 v[50:51], v[18:21], off sc1
	v_or_b32_e32 v17, v16, v32
	v_or_b32_e32 v16, v16, v33
	v_cvt_pk_bf16_f32 v18, v25, v23
	v_cvt_pk_bf16_f32 v19, v27, v41
	v_cvt_pk_bf16_f32 v20, v43, v45
	v_cvt_pk_bf16_f32 v21, v47, v49
	v_lshl_add_u64 v[22:23], v[14:15], 0, v[64:65]
	global_store_dwordx4 v[22:23], v[18:21], off sc1
	ds_read2_b32 v[22:23], v30 offset0:49 offset1:57
	ds_read2_b32 v[24:25], v30 offset0:16 offset1:24
	ds_read2_b32 v[26:27], v30 offset0:82 offset1:90
	ds_read2_b32 v[40:41], v30 offset0:115 offset1:123
	ds_read2_b32 v[42:43], v30 offset0:148 offset1:156
	ds_read2_b32 v[44:45], v30 offset0:181 offset1:189
	ds_read2_b32 v[46:47], v30 offset0:214 offset1:222
	ds_read2_b32 v[48:49], v30 offset0:247 offset1:255
	v_lshlrev_b32_e32 v64, 11, v17
	s_waitcnt lgkmcnt(6)
	v_cvt_pk_bf16_f32 v18, v24, v22
	s_waitcnt lgkmcnt(4)
	v_cvt_pk_bf16_f32 v19, v26, v40
	s_waitcnt lgkmcnt(2)
	v_cvt_pk_bf16_f32 v20, v42, v44
	s_waitcnt lgkmcnt(0)
	v_cvt_pk_bf16_f32 v21, v46, v48
	v_lshl_add_u64 v[50:51], v[14:15], 0, v[64:65]
	v_lshlrev_b32_e32 v64, 11, v16
	global_store_dwordx4 v[50:51], v[18:21], off sc1
	v_lshl_add_u64 v[14:15], v[14:15], 0, v[64:65]
	s_nop 0
	v_cvt_pk_bf16_f32 v18, v25, v23
	v_cvt_pk_bf16_f32 v19, v27, v41
	v_cvt_pk_bf16_f32 v20, v43, v45
	v_cvt_pk_bf16_f32 v21, v47, v49
	global_store_dwordx4 v[14:15], v[18:21], off sc1
	s_waitcnt lgkmcnt(0)

.LBB0_2253:
	s_andn2_saveexec_b64 s[6:7], s[6:7]
	s_cbranch_execz .LBB0_2255
	v_add_u32_e32 v15, 0x1400, v38
	v_and_b32_e32 v17, 0x1ffc0, v15
	v_and_b32_e32 v16, 0x3e0, v14
	v_or_b32_e32 v14, v17, v1
	v_lshlrev_b32_e32 v14, 10, v14
	v_or3_b32 v14, v14, v13, v16
	v_lshlrev_b32_e32 v64, 2, v14
	v_lshl_add_u64 v[14:15], s[12:13], 0, v[64:65]
	v_add_co_u32_e32 v18, vcc, 0x2000, v14
	s_mov_b32 s16, 0x10000
	s_nop 0
	v_addc_co_u32_e32 v19, vcc, 0, v15, vcc
	global_load_dword v21, v[18:19], off nt
	v_add_co_u32_e32 v18, vcc, 0x4000, v14
	global_load_dword v20, v64, s[12:13]
	s_nop 0
	v_addc_co_u32_e32 v19, vcc, 0, v15, vcc
	global_load_dword v22, v[18:19], off nt
	v_add_co_u32_e32 v18, vcc, 0x6000, v14
	s_nop 1
	v_addc_co_u32_e32 v19, vcc, 0, v15, vcc
	global_load_dword v23, v[18:19], off nt
	v_add_co_u32_e32 v18, vcc, 0x8000, v14
	s_nop 1
	v_addc_co_u32_e32 v19, vcc, 0, v15, vcc
	global_load_dword v24, v[18:19], off nt
	v_add_co_u32_e32 v18, vcc, 0xa000, v14
	s_nop 1
	v_addc_co_u32_e32 v19, vcc, 0, v15, vcc
	global_load_dword v25, v[18:19], off nt
	v_add_co_u32_e32 v18, vcc, 0xc000, v14
	s_nop 1
	v_addc_co_u32_e32 v19, vcc, 0, v15, vcc
	global_load_dword v26, v[18:19], off nt
	v_add_co_u32_e32 v18, vcc, 0xe000, v14
	s_nop 1
	v_addc_co_u32_e32 v19, vcc, 0, v15, vcc
	global_load_dword v27, v[18:19], off nt
	v_add_co_u32_e32 v18, vcc, s16, v14
	s_mov_b32 s16, 0x12000
	s_nop 0
	v_addc_co_u32_e32 v19, vcc, 0, v15, vcc
	global_load_dword v39, v[18:19], off nt
	v_add_co_u32_e32 v18, vcc, s16, v14
	s_mov_b32 s16, 0x14000
	s_nop 0
	v_addc_co_u32_e32 v19, vcc, 0, v15, vcc
	global_load_dword v40, v[18:19], off nt
	v_add_co_u32_e32 v18, vcc, s16, v14
	s_mov_b32 s16, 0x16000
	s_nop 0
	v_addc_co_u32_e32 v19, vcc, 0, v15, vcc
	global_load_dword v41, v[18:19], off nt
	v_add_co_u32_e32 v18, vcc, s16, v14
	s_mov_b32 s16, 0x18000
	s_nop 0
	v_addc_co_u32_e32 v19, vcc, 0, v15, vcc
	global_load_dword v42, v[18:19], off nt
	v_add_co_u32_e32 v18, vcc, s16, v14
	s_mov_b32 s16, 0x1a000
	s_nop 0
	v_addc_co_u32_e32 v19, vcc, 0, v15, vcc
	global_load_dword v43, v[18:19], off nt
	v_add_co_u32_e32 v18, vcc, s16, v14
	s_mov_b32 s16, 0x1c000
	s_nop 0
	v_addc_co_u32_e32 v19, vcc, 0, v15, vcc
	global_load_dword v44, v[18:19], off nt
	v_add_co_u32_e32 v18, vcc, s16, v14
	s_mov_b32 s16, 0x1e000
	s_nop 0
	v_addc_co_u32_e32 v19, vcc, 0, v15, vcc
	global_load_dword v45, v[18:19], off nt
	v_add_co_u32_e32 v18, vcc, s16, v14
	s_mov_b32 s16, 0x20000
	s_nop 0
	v_addc_co_u32_e32 v19, vcc, 0, v15, vcc
	global_load_dword v46, v[18:19], off nt
	v_add_co_u32_e32 v18, vcc, s16, v14
	s_mov_b32 s16, 0x22000
	s_nop 0
	v_addc_co_u32_e32 v19, vcc, 0, v15, vcc
	global_load_dword v47, v[18:19], off nt
	v_add_co_u32_e32 v18, vcc, s16, v14
	s_mov_b32 s16, 0x24000
	s_nop 0
	v_addc_co_u32_e32 v19, vcc, 0, v15, vcc
	global_load_dword v48, v[18:19], off nt
	v_add_co_u32_e32 v18, vcc, s16, v14
	s_mov_b32 s16, 0x26000
	s_nop 0
	v_addc_co_u32_e32 v19, vcc, 0, v15, vcc
	global_load_dword v49, v[18:19], off nt
	v_add_co_u32_e32 v18, vcc, s16, v14
	s_mov_b32 s16, 0x28000
	s_nop 0
	v_addc_co_u32_e32 v19, vcc, 0, v15, vcc
	global_load_dword v50, v[18:19], off nt
	v_add_co_u32_e32 v18, vcc, s16, v14
	s_mov_b32 s16, 0x2a000
	s_nop 0
	v_addc_co_u32_e32 v19, vcc, 0, v15, vcc
	global_load_dword v51, v[18:19], off nt
	v_add_co_u32_e32 v18, vcc, s16, v14
	s_mov_b32 s16, 0x2c000
	s_nop 0
	v_addc_co_u32_e32 v19, vcc, 0, v15, vcc
	global_load_dword v52, v[18:19], off nt
	v_add_co_u32_e32 v18, vcc, s16, v14
	s_mov_b32 s16, 0x2e000
	s_nop 0
	v_addc_co_u32_e32 v19, vcc, 0, v15, vcc
	global_load_dword v53, v[18:19], off nt
	v_add_co_u32_e32 v18, vcc, s16, v14
	s_mov_b32 s16, 0x30000
	s_nop 0
	v_addc_co_u32_e32 v19, vcc, 0, v15, vcc
	global_load_dword v54, v[18:19], off nt
	v_add_co_u32_e32 v18, vcc, s16, v14
	s_mov_b32 s16, 0x32000
	s_nop 0
	v_addc_co_u32_e32 v19, vcc, 0, v15, vcc
	global_load_dword v55, v[18:19], off nt
	v_add_co_u32_e32 v18, vcc, s16, v14
	s_mov_b32 s16, 0x34000
	s_nop 0
	v_addc_co_u32_e32 v19, vcc, 0, v15, vcc
	global_load_dword v56, v[18:19], off nt
	v_add_co_u32_e32 v18, vcc, s16, v14
	s_mov_b32 s16, 0x36000
	s_nop 0
	v_addc_co_u32_e32 v19, vcc, 0, v15, vcc
	global_load_dword v57, v[18:19], off nt
	v_add_co_u32_e32 v18, vcc, s16, v14
	s_mov_b32 s16, 0x38000
	s_nop 0
	v_addc_co_u32_e32 v19, vcc, 0, v15, vcc
	global_load_dword v58, v[18:19], off nt
	v_add_co_u32_e32 v18, vcc, s16, v14
	s_mov_b32 s16, 0x3a000
	s_nop 0
	v_addc_co_u32_e32 v19, vcc, 0, v15, vcc
	global_load_dword v59, v[18:19], off nt
	v_add_co_u32_e32 v18, vcc, s16, v14
	s_mov_b32 s16, 0x3c000
	s_nop 0
	v_addc_co_u32_e32 v19, vcc, 0, v15, vcc
	global_load_dword v60, v[18:19], off nt
	v_add_co_u32_e32 v18, vcc, s16, v14
	s_mov_b32 s16, 0x3e000
	s_nop 0
	v_addc_co_u32_e32 v19, vcc, 0, v15, vcc
	v_add_co_u32_e32 v14, vcc, s16, v14
	global_load_dword v18, v[18:19], off nt
	s_nop 0
	v_addc_co_u32_e32 v15, vcc, 0, v15, vcc
	global_load_dword v14, v[14:15], off nt
	v_add_u32_e32 v15, 0x400, v28
	s_waitcnt vmcnt(0)
	ds_write2_b32 v28, v20, v21 offset1:66
	ds_write2_b32 v28, v22, v23 offset0:132 offset1:198
	ds_write2_b32 v15, v24, v25 offset0:8 offset1:74
	ds_write2_b32 v15, v26, v27 offset0:140 offset1:206
	v_add_u32_e32 v15, 0x800, v28
	ds_write2_b32 v15, v39, v40 offset0:16 offset1:82
	ds_write2_b32 v15, v41, v42 offset0:148 offset1:214
	v_add_u32_e32 v15, 0xc00, v28
	ds_write2_b32 v15, v43, v44 offset0:24 offset1:90
	ds_write2_b32 v15, v45, v46 offset0:156 offset1:222
	v_add_u32_e32 v15, 0x1000, v28
	ds_write2_b32 v15, v47, v48 offset0:32 offset1:98
	ds_write2_b32 v15, v49, v50 offset0:164 offset1:230
	v_add_u32_e32 v15, 0x1400, v28
	ds_write2_b32 v15, v51, v52 offset0:40 offset1:106
	ds_write2_b32 v15, v53, v54 offset0:172 offset1:238
	v_add_u32_e32 v15, 0x1800, v28
	ds_write2_b32 v15, v55, v56 offset0:48 offset1:114
	ds_write2_b32 v15, v57, v58 offset0:180 offset1:246
	v_add_u32_e32 v15, 0x1c00, v28
	ds_write2_b32 v15, v59, v60 offset0:56 offset1:122
	ds_write2_b32 v15, v18, v14 offset0:188 offset1:254
	s_waitcnt lgkmcnt(0)
	ds_read2_b32 v[22:23], v30 offset0:33 offset1:41
	ds_read2_b32 v[24:25], v30 offset1:8
	ds_read2_b32 v[26:27], v30 offset0:66 offset1:74
	ds_read2_b32 v[40:41], v30 offset0:99 offset1:107
	ds_read2_b32 v[42:43], v30 offset0:132 offset1:140
	ds_read2_b32 v[44:45], v30 offset0:165 offset1:173
	ds_read2_b32 v[46:47], v30 offset0:198 offset1:206
	ds_read2_b32 v[48:49], v30 offset0:231 offset1:239
	v_lshlrev_b32_e32 v64, 1, v17
	v_or_b32_e32 v17, v16, v29
	v_lshl_add_u64 v[14:15], v[6:7], 0, v[64:65]
	v_lshlrev_b32_e32 v64, 11, v17
	v_or_b32_e32 v17, v16, v31
	s_waitcnt lgkmcnt(0)
	v_cvt_pk_bf16_f32 v18, v24, v22
	v_cvt_pk_bf16_f32 v19, v26, v40
	v_cvt_pk_bf16_f32 v20, v42, v44
	v_cvt_pk_bf16_f32 v21, v46, v48
	v_lshl_add_u64 v[50:51], v[14:15], 0, v[64:65]
	v_lshlrev_b32_e32 v64, 11, v17
	global_store_dwordx4 v[50:51], v[18:21], off sc1
	v_or_b32_e32 v17, v16, v32
	v_or_b32_e32 v16, v16, v33
	v_cvt_pk_bf16_f32 v18, v25, v23
	v_cvt_pk_bf16_f32 v19, v27, v41
	v_cvt_pk_bf16_f32 v20, v43, v45
	v_cvt_pk_bf16_f32 v21, v47, v49
	v_lshl_add_u64 v[22:23], v[14:15], 0, v[64:65]
	global_store_dwordx4 v[22:23], v[18:21], off sc1
	ds_read2_b32 v[22:23], v30 offset0:49 offset1:57
	ds_read2_b32 v[24:25], v30 offset0:16 offset1:24
	ds_read2_b32 v[26:27], v30 offset0:82 offset1:90
	ds_read2_b32 v[40:41], v30 offset0:115 offset1:123
	ds_read2_b32 v[42:43], v30 offset0:148 offset1:156
	ds_read2_b32 v[44:45], v30 offset0:181 offset1:189
	ds_read2_b32 v[46:47], v30 offset0:214 offset1:222
	ds_read2_b32 v[48:49], v30 offset0:247 offset1:255
	v_lshlrev_b32_e32 v64, 11, v17
	s_waitcnt lgkmcnt(6)
	v_cvt_pk_bf16_f32 v18, v24, v22
	s_waitcnt lgkmcnt(4)
	v_cvt_pk_bf16_f32 v19, v26, v40
	s_waitcnt lgkmcnt(2)
	v_cvt_pk_bf16_f32 v20, v42, v44
	s_waitcnt lgkmcnt(0)
	v_cvt_pk_bf16_f32 v21, v46, v48
	v_lshl_add_u64 v[50:51], v[14:15], 0, v[64:65]
	v_lshlrev_b32_e32 v64, 11, v16
	global_store_dwordx4 v[50:51], v[18:21], off sc1
	v_lshl_add_u64 v[14:15], v[14:15], 0, v[64:65]
	s_nop 0
	v_cvt_pk_bf16_f32 v18, v25, v23
	v_cvt_pk_bf16_f32 v19, v27, v41
	v_cvt_pk_bf16_f32 v20, v43, v45
	v_cvt_pk_bf16_f32 v21, v47, v49
	global_store_dwordx4 v[14:15], v[18:21], off sc1
	s_waitcnt lgkmcnt(0)

.LBB0_2256:
	s_andn2_saveexec_b64 s[16:17], s[4:5]
	s_cbranch_execz .LBB0_2245
	s_mov_b32 s4, 0x2e8ba2e9
	v_mul_hi_i32 v14, v0, s4
	v_lshrrev_b32_e32 v15, 31, v14
	v_ashrrev_i32_e32 v14, 4, v14
	v_add_u32_e32 v15, v14, v15
	s_movk_i32 s4, 0xffa8
	v_mad_u64_u32 v[20:21], s[4:5], v15, s4, v[0:1]
	s_movk_i32 s4, 0xf500
	s_nop 0
	v_mad_u64_u32 v[18:19], s[4:5], v15, s4, v[12:13]
	v_add_u32_e32 v16, 0x600, v18
	v_lshlrev_b32_e32 v14, 6, v15
	v_ashrrev_i32_e32 v17, 31, v16
	v_or_b32_e32 v15, v14, v1
	v_lshl_add_u64 v[22:23], v[16:17], 2, v[10:11]
	v_mad_i64_i32 v[24:25], s[4:5], v15, s78, v[22:23]
	v_or_b32_e32 v19, 2, v15
	global_load_dword v17, v[24:25], off nt
	v_mad_i64_i32 v[24:25], s[4:5], v19, s78, v[22:23]
	v_or_b32_e32 v21, 4, v15
	global_load_dword v19, v[24:25], off nt
	v_mad_i64_i32 v[24:25], s[4:5], v21, s78, v[22:23]
	global_load_dword v21, v[24:25], off nt
	v_or_b32_e32 v24, 6, v15
	v_mad_i64_i32 v[24:25], s[4:5], v24, s78, v[22:23]
	global_load_dword v26, v[24:25], off nt
	v_or_b32_e32 v24, 8, v15
	v_mad_i64_i32 v[24:25], s[4:5], v24, s78, v[22:23]
	global_load_dword v27, v[24:25], off nt
	v_or_b32_e32 v24, 10, v15
	v_mad_i64_i32 v[24:25], s[4:5], v24, s78, v[22:23]
	global_load_dword v39, v[24:25], off nt
	v_or_b32_e32 v24, 12, v15
	v_mad_i64_i32 v[24:25], s[4:5], v24, s78, v[22:23]
	global_load_dword v40, v[24:25], off nt
	v_or_b32_e32 v24, 14, v15
	v_mad_i64_i32 v[24:25], s[4:5], v24, s78, v[22:23]
	global_load_dword v41, v[24:25], off nt
	v_or_b32_e32 v24, 16, v15
	v_mad_i64_i32 v[24:25], s[4:5], v24, s78, v[22:23]
	global_load_dword v42, v[24:25], off nt
	v_or_b32_e32 v24, 18, v15
	v_mad_i64_i32 v[24:25], s[4:5], v24, s78, v[22:23]
	global_load_dword v43, v[24:25], off nt
	v_or_b32_e32 v24, 20, v15
	v_mad_i64_i32 v[24:25], s[4:5], v24, s78, v[22:23]
	global_load_dword v44, v[24:25], off nt
	v_or_b32_e32 v24, 22, v15
	v_mad_i64_i32 v[24:25], s[4:5], v24, s78, v[22:23]
	global_load_dword v45, v[24:25], off nt
	v_or_b32_e32 v24, 24, v15
	v_mad_i64_i32 v[24:25], s[4:5], v24, s78, v[22:23]
	global_load_dword v46, v[24:25], off nt
	v_or_b32_e32 v24, 26, v15
	v_mad_i64_i32 v[24:25], s[4:5], v24, s78, v[22:23]
	global_load_dword v47, v[24:25], off nt
	v_or_b32_e32 v24, 28, v15
	v_mad_i64_i32 v[24:25], s[4:5], v24, s78, v[22:23]
	global_load_dword v48, v[24:25], off nt
	v_or_b32_e32 v24, 30, v15
	v_mad_i64_i32 v[24:25], s[4:5], v24, s78, v[22:23]
	global_load_dword v49, v[24:25], off nt
	v_or_b32_e32 v24, 32, v15
	v_mad_i64_i32 v[24:25], s[4:5], v24, s78, v[22:23]
	global_load_dword v50, v[24:25], off nt
	v_or_b32_e32 v24, 34, v15
	v_mad_i64_i32 v[24:25], s[4:5], v24, s78, v[22:23]
	global_load_dword v51, v[24:25], off nt
	v_or_b32_e32 v24, 36, v15
	v_mad_i64_i32 v[24:25], s[4:5], v24, s78, v[22:23]
	global_load_dword v52, v[24:25], off nt
	v_or_b32_e32 v24, 38, v15
	v_mad_i64_i32 v[24:25], s[4:5], v24, s78, v[22:23]
	global_load_dword v53, v[24:25], off nt
	v_or_b32_e32 v24, 40, v15
	v_mad_i64_i32 v[24:25], s[4:5], v24, s78, v[22:23]
	global_load_dword v54, v[24:25], off nt
	v_or_b32_e32 v24, 42, v15
	v_mad_i64_i32 v[24:25], s[4:5], v24, s78, v[22:23]
	global_load_dword v55, v[24:25], off nt
	v_or_b32_e32 v24, 44, v15
	v_mad_i64_i32 v[24:25], s[4:5], v24, s78, v[22:23]
	global_load_dword v56, v[24:25], off nt
	v_or_b32_e32 v24, 46, v15
	v_mad_i64_i32 v[24:25], s[4:5], v24, s78, v[22:23]
	global_load_dword v57, v[24:25], off nt
	v_or_b32_e32 v24, 48, v15
	v_mad_i64_i32 v[24:25], s[4:5], v24, s78, v[22:23]
	global_load_dword v58, v[24:25], off nt
	v_or_b32_e32 v24, 50, v15
	v_mad_i64_i32 v[24:25], s[4:5], v24, s78, v[22:23]
	global_load_dword v59, v[24:25], off nt
	v_or_b32_e32 v24, 52, v15
	v_mad_i64_i32 v[24:25], s[4:5], v24, s78, v[22:23]
	global_load_dword v60, v[24:25], off nt
	v_or_b32_e32 v24, 54, v15
	v_mad_i64_i32 v[24:25], s[4:5], v24, s78, v[22:23]
	global_load_dword v61, v[24:25], off nt
	v_or_b32_e32 v24, 56, v15
	v_mad_i64_i32 v[24:25], s[4:5], v24, s78, v[22:23]
	global_load_dword v62, v[24:25], off nt
	v_or_b32_e32 v24, 58, v15
	v_mad_i64_i32 v[24:25], s[4:5], v24, s78, v[22:23]
	global_load_dword v63, v[24:25], off nt
	v_or_b32_e32 v24, 60, v15
	v_or_b32_e32 v15, 62, v15
	v_mad_i64_i32 v[24:25], s[4:5], v24, s78, v[22:23]
	v_mad_i64_i32 v[22:23], s[4:5], v15, s78, v[22:23]
	global_load_dword v24, v[24:25], off nt
	s_movk_i32 s4, 0x17f
	global_load_dword v15, v[22:23], off nt
	s_waitcnt vmcnt(0)
	ds_write2_b32 v28, v17, v19 offset1:66
	ds_write2_b32 v28, v21, v26 offset0:132 offset1:198
	v_add_u32_e32 v17, 0x400, v28
	ds_write2_b32 v17, v27, v39 offset0:8 offset1:74
	ds_write2_b32 v17, v40, v41 offset0:140 offset1:206
	v_add_u32_e32 v17, 0x800, v28
	ds_write2_b32 v17, v42, v43 offset0:16 offset1:82
	ds_write2_b32 v17, v44, v45 offset0:148 offset1:214
	v_add_u32_e32 v17, 0xc00, v28
	ds_write2_b32 v17, v46, v47 offset0:24 offset1:90
	ds_write2_b32 v17, v48, v49 offset0:156 offset1:222
	v_add_u32_e32 v17, 0x1000, v28
	ds_write2_b32 v17, v50, v51 offset0:32 offset1:98
	ds_write2_b32 v17, v52, v53 offset0:164 offset1:230
	v_add_u32_e32 v17, 0x1400, v28
	ds_write2_b32 v17, v54, v55 offset0:40 offset1:106
	ds_write2_b32 v17, v56, v57 offset0:172 offset1:238
	v_add_u32_e32 v17, 0x1800, v28
	ds_write2_b32 v17, v58, v59 offset0:48 offset1:114
	ds_write2_b32 v17, v60, v61 offset0:180 offset1:246
	v_add_u32_e32 v17, 0x1c00, v28
	ds_write2_b32 v17, v62, v63 offset0:56 offset1:122
	ds_write2_b32 v17, v24, v15 offset0:188 offset1:254
	s_waitcnt lgkmcnt(0)
	v_and_b32_e32 v15, 0x7fffff0, v20
	ds_read2_b32 v[20:21], v30 offset1:33
	ds_read2_b32 v[22:23], v30 offset0:66 offset1:99
	ds_read2_b32 v[24:25], v30 offset0:132 offset1:165
	ds_read2_b32 v[26:27], v30 offset0:198 offset1:231
	v_add_u32_e32 v41, v18, v29
	v_cmp_eq_u32_e32 vcc, 64, v15
	v_and_b32_e32 v39, 0x9e0, v16
	v_add_u32_e32 v15, 0x600, v41
	v_cmp_lt_u32_e64 s[4:5], s4, v18
	s_and_saveexec_b64 s[6:7], s[4:5]
	s_xor_b64 s[6:7], exec, s[6:7]
	v_or_b32_e32 v17, v39, v34
	v_cndmask_b32_e32 v18, v15, v17, vcc
	s_or_saveexec_b64 s[18:19], s[6:7]
	v_and_b32_e32 v40, 0x7c0, v16
	s_xor_b64 exec, exec, s[18:19]
	v_and_b32_e32 v15, 39, v15
	v_lshlrev_b32_e32 v16, 1, v15
	v_subrev_u32_e32 v17, 63, v16
	v_cmp_gt_u32_e64 s[6:7], 32, v15
	s_nop 1
	v_cndmask_b32_e64 v15, v17, v16, s[6:7]
	v_add_u32_e32 v18, v15, v40
	s_or_b64 exec, exec, s[18:19]
	v_ashrrev_i32_e32 v15, 31, v14
	v_ashrrev_i32_e32 v19, 31, v18
	v_lshl_add_u64 v[14:15], v[14:15], 1, v[8:9]
	v_lshlrev_b64 v[16:17], 11, v[18:19]
	s_waitcnt lgkmcnt(0)
	v_cvt_pk_bf16_f32 v20, v20, v21
	v_cvt_pk_bf16_f32 v21, v22, v23
	v_cvt_pk_bf16_f32 v22, v24, v25
	v_cvt_pk_bf16_f32 v23, v26, v27
	v_lshl_add_u64 v[16:17], v[14:15], 0, v[16:17]
	global_store_dwordx4 v[16:17], v[20:23], off sc1
	ds_read2_b32 v[16:17], v30 offset0:8 offset1:41
	ds_read2_b32 v[18:19], v30 offset0:74 offset1:107
	ds_read2_b32 v[20:21], v30 offset0:140 offset1:173
	ds_read2_b32 v[22:23], v30 offset0:206 offset1:239
	v_add_u32_e32 v25, 0x608, v41
	s_and_saveexec_b64 s[6:7], s[4:5]
	s_xor_b64 s[6:7], exec, s[6:7]
	v_or_b32_e32 v24, v39, v35
	v_cndmask_b32_e32 v24, v25, v24, vcc
	s_andn2_saveexec_b64 s[18:19], s[6:7]
	v_and_b32_e32 v24, 47, v25
	v_lshlrev_b32_e32 v25, 1, v24
	v_subrev_u32_e32 v26, 63, v25
	v_cmp_gt_u32_e64 s[6:7], 32, v24
	s_nop 1
	v_cndmask_b32_e64 v24, v26, v25, s[6:7]
	v_add_u32_e32 v24, v24, v40
	s_or_b64 exec, exec, s[18:19]
	v_ashrrev_i32_e32 v25, 31, v24
	s_waitcnt lgkmcnt(3)
	v_cvt_pk_bf16_f32 v16, v16, v17
	s_waitcnt lgkmcnt(2)
	v_cvt_pk_bf16_f32 v17, v18, v19
	s_waitcnt lgkmcnt(1)
	v_cvt_pk_bf16_f32 v18, v20, v21
	v_lshlrev_b64 v[20:21], 11, v[24:25]
	s_waitcnt lgkmcnt(0)
	v_cvt_pk_bf16_f32 v19, v22, v23
	v_lshl_add_u64 v[20:21], v[14:15], 0, v[20:21]
	global_store_dwordx4 v[20:21], v[16:19], off sc1
	ds_read2_b32 v[16:17], v30 offset0:16 offset1:49
	ds_read2_b32 v[18:19], v30 offset0:82 offset1:115
	ds_read2_b32 v[20:21], v30 offset0:148 offset1:181
	ds_read2_b32 v[22:23], v30 offset0:214 offset1:247
	v_add_u32_e32 v25, 0x610, v41
	s_and_saveexec_b64 s[6:7], s[4:5]
	s_xor_b64 s[6:7], exec, s[6:7]
	v_or_b32_e32 v24, v39, v36
	v_cndmask_b32_e32 v24, v25, v24, vcc
	s_andn2_saveexec_b64 s[18:19], s[6:7]
	v_and_b32_e32 v24, 55, v25
	v_lshlrev_b32_e32 v25, 1, v24
	v_subrev_u32_e32 v26, 63, v25
	v_cmp_gt_u32_e64 s[6:7], 32, v24
	s_nop 1
	v_cndmask_b32_e64 v24, v26, v25, s[6:7]
	v_add_u32_e32 v24, v24, v40
	s_or_b64 exec, exec, s[18:19]
	v_ashrrev_i32_e32 v25, 31, v24
	s_waitcnt lgkmcnt(3)
	v_cvt_pk_bf16_f32 v16, v16, v17
	s_waitcnt lgkmcnt(2)
	v_cvt_pk_bf16_f32 v17, v18, v19
	s_waitcnt lgkmcnt(1)
	v_cvt_pk_bf16_f32 v18, v20, v21
	v_lshlrev_b64 v[20:21], 11, v[24:25]
	s_waitcnt lgkmcnt(0)
	v_cvt_pk_bf16_f32 v19, v22, v23
	v_lshl_add_u64 v[20:21], v[14:15], 0, v[20:21]
	global_store_dwordx4 v[20:21], v[16:19], off sc1
	ds_read2_b32 v[16:17], v30 offset0:24 offset1:57
	ds_read2_b32 v[18:19], v30 offset0:90 offset1:123
	ds_read2_b32 v[20:21], v30 offset0:156 offset1:189
	ds_read2_b32 v[22:23], v30 offset0:222 offset1:255
	v_add_u32_e32 v25, 0x618, v41
	s_and_saveexec_b64 s[6:7], s[4:5]
	s_xor_b64 s[4:5], exec, s[6:7]
	v_or_b32_e32 v24, v39, v37
	v_cndmask_b32_e32 v24, v25, v24, vcc
	s_andn2_saveexec_b64 s[4:5], s[4:5]
	s_cbranch_execz .LBB0_2244
	v_and_b32_e32 v24, 63, v25
	v_lshlrev_b32_e32 v25, 1, v24
	v_subrev_u32_e32 v26, 63, v25
	v_cmp_gt_u32_e32 vcc, 32, v24
	s_nop 1
	v_cndmask_b32_e32 v24, v26, v25, vcc
	v_add_u32_e32 v24, v24, v40
	s_branch .LBB0_2244
